# selfmax + GEMM K-loop: address VALU at the head of SP2 load segments moved behind the LDS fragment reads
# baseline (speedup 1.0000x reference)
.LBB0_138:
	ds_read_b128 v[148:151], v157
	ds_read_b128 v[162:165], v157 offset:1024
	ds_read_b128 v[166:169], v157 offset:2048
	ds_read_b128 v[170:173], v157 offset:3072
	ds_read_b128 v[174:177], v158
	ds_read_b128 v[178:181], v158 offset:1024
	ds_read_b128 v[182:185], v158 offset:2048
	ds_read_b128 v[186:189], v158 offset:3072
	s_add_u32 s12, s10, 0xfffc0080
	s_addc_u32 s13, s11, -1
	s_cmp_eq_u32 s84, 12
	s_cselect_b32 s15, s7, s13
	s_cselect_b32 s14, s9, s12
	s_cselect_b32 s13, s20, s35
	s_cselect_b32 s12, s21, s31
	v_lshl_add_u64 v[152:153], s[10:11], 0, v[140:141]
	s_add_i32 m0, s97, 0xc000
	ds_read_b128 v[190:193], v159
	ds_read_b128 v[194:197], v159 offset:1024
	ds_read_b128 v[198:201], v159 offset:2048
	ds_read_b128 v[202:205], v159 offset:3072
	ds_read_b128 v[206:209], v159 offset:4096
	ds_read_b128 v[210:213], v159 offset:5120
	ds_read_b128 v[214:217], v159 offset:6144
	ds_read_b128 v[218:221], v159 offset:7168
	global_load_lds_dwordx4 v[152:153], off
	v_lshl_add_u64 v[152:153], s[10:11], 0, v[142:143]
	s_add_i32 m0, s97, 0xe000
	s_nop 0
	global_load_lds_dwordx4 v[152:153], off
	s_waitcnt vmcnt(8)
	s_waitcnt lgkmcnt(0)
	s_barrier
	s_setprio 1
	s_waitcnt lgkmcnt(0)
	v_mfma_f32_16x16x32_bf16 v[126:129], v[148:151], v[190:193], v[126:129]
	v_mfma_f32_16x16x32_bf16 v[122:125], v[166:169], v[190:193], v[122:125]
	v_mfma_f32_16x16x32_bf16 v[110:113], v[148:151], v[198:201], v[110:113]
	v_mfma_f32_16x16x32_bf16 v[106:109], v[166:169], v[198:201], v[106:109]
	v_mfma_f32_16x16x32_bf16 v[94:97], v[148:151], v[206:209], v[94:97]
	v_mfma_f32_16x16x32_bf16 v[90:93], v[166:169], v[206:209], v[90:93]
	v_mfma_f32_16x16x32_bf16 v[78:81], v[148:151], v[214:217], v[78:81]
	v_mfma_f32_16x16x32_bf16 v[74:77], v[166:169], v[214:217], v[74:77]
	v_mfma_f32_16x16x32_bf16 v[126:129], v[162:165], v[194:197], v[126:129]
	v_mfma_f32_16x16x32_bf16 v[122:125], v[170:173], v[194:197], v[122:125]
	v_mfma_f32_16x16x32_bf16 v[110:113], v[162:165], v[202:205], v[110:113]
	v_mfma_f32_16x16x32_bf16 v[106:109], v[170:173], v[202:205], v[106:109]
	v_mfma_f32_16x16x32_bf16 v[94:97], v[162:165], v[210:213], v[94:97]
	v_mfma_f32_16x16x32_bf16 v[90:93], v[170:173], v[210:213], v[90:93]
	v_mfma_f32_16x16x32_bf16 v[78:81], v[162:165], v[218:221], v[78:81]
	v_mfma_f32_16x16x32_bf16 v[74:77], v[170:173], v[218:221], v[74:77]
	s_setprio 0
	s_setprio 1
	v_mfma_f32_16x16x32_bf16 v[118:121], v[174:177], v[190:193], v[118:121]
	v_mfma_f32_16x16x32_bf16 v[114:117], v[182:185], v[190:193], v[114:117]
	v_mfma_f32_16x16x32_bf16 v[102:105], v[174:177], v[198:201], v[102:105]
	v_mfma_f32_16x16x32_bf16 v[98:101], v[182:185], v[198:201], v[98:101]
	v_mfma_f32_16x16x32_bf16 v[86:89], v[174:177], v[206:209], v[86:89]
	v_mfma_f32_16x16x32_bf16 v[82:85], v[182:185], v[206:209], v[82:85]
	v_mfma_f32_16x16x32_bf16 v[70:73], v[174:177], v[214:217], v[70:73]
	v_mfma_f32_16x16x32_bf16 v[66:69], v[182:185], v[214:217], v[66:69]
	v_mfma_f32_16x16x32_bf16 v[118:121], v[178:181], v[194:197], v[118:121]
	v_mfma_f32_16x16x32_bf16 v[114:117], v[186:189], v[194:197], v[114:117]
	v_mfma_f32_16x16x32_bf16 v[102:105], v[178:181], v[202:205], v[102:105]
	v_mfma_f32_16x16x32_bf16 v[98:101], v[186:189], v[202:205], v[98:101]
	v_mfma_f32_16x16x32_bf16 v[86:89], v[178:181], v[210:213], v[86:89]
	v_mfma_f32_16x16x32_bf16 v[82:85], v[186:189], v[210:213], v[82:85]
	v_mfma_f32_16x16x32_bf16 v[70:73], v[178:181], v[218:221], v[70:73]
	v_mfma_f32_16x16x32_bf16 v[66:69], v[186:189], v[218:221], v[66:69]
	s_setprio 0
	s_barrier
	s_add_i32 s85, s90, s96
	s_mov_b32 m0, s85
	ds_read_b128 v[190:193], v159 offset:16384
	ds_read_b128 v[194:197], v159 offset:17408
	ds_read_b128 v[198:201], v159 offset:18432
	ds_read_b128 v[202:205], v159 offset:19456
	ds_read_b128 v[206:209], v159 offset:20480
	ds_read_b128 v[210:213], v159 offset:21504
	ds_read_b128 v[214:217], v159 offset:22528
	ds_read_b128 v[218:221], v159 offset:23552
	v_lshl_add_u64 v[152:153], s[12:13], 0, v[132:133]
	global_load_lds_dwordx4 v[152:153], off
	s_add_i32 m0, s85, 0x2000
	s_add_u32 s86, s12, 0x40000
	v_lshl_add_u64 v[222:223], s[12:13], 0, v[136:137]
	s_addc_u32 s87, s13, 0
	s_add_i32 s85, s91, s96
	global_load_lds_dwordx4 v[222:223], off
	v_lshl_add_u64 v[224:225], s[86:87], 0, v[132:133]
	s_mov_b32 m0, s85
	v_lshl_add_u64 v[226:227], s[14:15], 0, v[134:135]
	global_load_lds_dwordx4 v[224:225], off
	v_lshl_add_u64 v[224:225], s[86:87], 0, v[136:137]
	s_add_i32 m0, s85, 0x2000
	s_nop 0
	global_load_lds_dwordx4 v[224:225], off
	v_lshl_add_u64 v[224:225], s[14:15], 0, v[130:131]
	s_mov_b32 m0, s97
	s_nop 0
	global_load_lds_dwordx4 v[224:225], off
	s_mov_b32 m0, s16
	s_nop 0
	global_load_lds_dwordx4 v[226:227], off
	s_waitcnt vmcnt(8)
	s_waitcnt lgkmcnt(0)
	s_barrier
	s_setprio 1
	s_waitcnt lgkmcnt(0)
	v_mfma_f32_16x16x32_bf16 v[62:65], v[148:151], v[190:193], v[62:65]
	v_mfma_f32_16x16x32_bf16 v[58:61], v[166:169], v[190:193], v[58:61]
	v_mfma_f32_16x16x32_bf16 v[46:49], v[148:151], v[198:201], v[46:49]
	v_mfma_f32_16x16x32_bf16 v[42:45], v[166:169], v[198:201], v[42:45]
	v_mfma_f32_16x16x32_bf16 v[30:33], v[148:151], v[206:209], v[30:33]
	v_mfma_f32_16x16x32_bf16 v[26:29], v[166:169], v[206:209], v[26:29]
	v_mfma_f32_16x16x32_bf16 v[14:17], v[148:151], v[214:217], v[14:17]
	v_mfma_f32_16x16x32_bf16 v[10:13], v[166:169], v[214:217], v[10:13]
	v_mfma_f32_16x16x32_bf16 v[62:65], v[162:165], v[194:197], v[62:65]
	v_mfma_f32_16x16x32_bf16 v[58:61], v[170:173], v[194:197], v[58:61]
	v_mfma_f32_16x16x32_bf16 v[46:49], v[162:165], v[202:205], v[46:49]
	v_mfma_f32_16x16x32_bf16 v[42:45], v[170:173], v[202:205], v[42:45]
	v_mfma_f32_16x16x32_bf16 v[30:33], v[162:165], v[210:213], v[30:33]
	v_mfma_f32_16x16x32_bf16 v[26:29], v[170:173], v[210:213], v[26:29]
	v_mfma_f32_16x16x32_bf16 v[14:17], v[162:165], v[218:221], v[14:17]
	v_mfma_f32_16x16x32_bf16 v[10:13], v[170:173], v[218:221], v[10:13]
	s_setprio 0
	s_setprio 1
	v_mfma_f32_16x16x32_bf16 v[54:57], v[174:177], v[190:193], v[54:57]
	v_mfma_f32_16x16x32_bf16 v[50:53], v[182:185], v[190:193], v[50:53]
	v_mfma_f32_16x16x32_bf16 v[38:41], v[174:177], v[198:201], v[38:41]
	v_mfma_f32_16x16x32_bf16 v[34:37], v[182:185], v[198:201], v[34:37]
	v_mfma_f32_16x16x32_bf16 v[22:25], v[174:177], v[206:209], v[22:25]
	v_mfma_f32_16x16x32_bf16 v[18:21], v[182:185], v[206:209], v[18:21]
	v_mfma_f32_16x16x32_bf16 v[6:9], v[174:177], v[214:217], v[6:9]
	v_mfma_f32_16x16x32_bf16 v[2:5], v[182:185], v[214:217], v[2:5]
	v_mfma_f32_16x16x32_bf16 v[54:57], v[178:181], v[194:197], v[54:57]
	v_mfma_f32_16x16x32_bf16 v[50:53], v[186:189], v[194:197], v[50:53]
	v_mfma_f32_16x16x32_bf16 v[38:41], v[178:181], v[202:205], v[38:41]
	v_mfma_f32_16x16x32_bf16 v[34:37], v[186:189], v[202:205], v[34:37]
	v_mfma_f32_16x16x32_bf16 v[22:25], v[178:181], v[210:213], v[22:25]
	v_mfma_f32_16x16x32_bf16 v[18:21], v[186:189], v[210:213], v[18:21]
	v_mfma_f32_16x16x32_bf16 v[6:9], v[178:181], v[218:221], v[6:9]
	v_mfma_f32_16x16x32_bf16 v[2:5], v[186:189], v[218:221], v[2:5]
	s_setprio 0
	s_barrier
	s_add_i32 s85, 0, 0x18000
	v_add_u32_e32 v138, s85, v155
	s_add_i32 s86, 0, 0x1c000
	ds_read_b128 v[148:151], v138
	ds_read_b128 v[162:165], v138 offset:1024
	ds_read_b128 v[166:169], v138 offset:2048
	ds_read_b128 v[170:173], v138 offset:3072
	v_add_u32_e32 v138, s86, v155
	ds_read_b128 v[174:177], v138
	ds_read_b128 v[178:181], v138 offset:1024
	ds_read_b128 v[182:185], v138 offset:2048
	ds_read_b128 v[186:189], v138 offset:3072
	s_add_u32 s14, s14, 0x40000
	s_addc_u32 s15, s15, 0
	s_mov_b32 m0, s17
	v_lshl_add_u64 v[228:229], s[14:15], 0, v[130:131]
	ds_read_b128 v[190:193], v159 offset:32768
	ds_read_b128 v[194:197], v159 offset:33792
	ds_read_b128 v[198:201], v159 offset:34816
	ds_read_b128 v[202:205], v159 offset:35840
	ds_read_b128 v[206:209], v159 offset:36864
	ds_read_b128 v[210:213], v159 offset:37888
	ds_read_b128 v[214:217], v159 offset:38912
	ds_read_b128 v[218:221], v159 offset:39936
	global_load_lds_dwordx4 v[228:229], off
	v_lshl_add_u64 v[228:229], s[14:15], 0, v[134:135]
	s_mov_b32 m0, s27
	s_nop 0
	global_load_lds_dwordx4 v[228:229], off
	s_waitcnt vmcnt(8)
	s_waitcnt lgkmcnt(0)
	s_barrier
	s_setprio 1
	s_waitcnt lgkmcnt(0)
	v_mfma_f32_16x16x32_bf16 v[126:129], v[148:151], v[190:193], v[126:129]
	v_mfma_f32_16x16x32_bf16 v[122:125], v[166:169], v[190:193], v[122:125]
	v_mfma_f32_16x16x32_bf16 v[110:113], v[148:151], v[198:201], v[110:113]
	v_mfma_f32_16x16x32_bf16 v[106:109], v[166:169], v[198:201], v[106:109]
	v_mfma_f32_16x16x32_bf16 v[94:97], v[148:151], v[206:209], v[94:97]
	v_mfma_f32_16x16x32_bf16 v[90:93], v[166:169], v[206:209], v[90:93]
	v_mfma_f32_16x16x32_bf16 v[78:81], v[148:151], v[214:217], v[78:81]
	v_mfma_f32_16x16x32_bf16 v[74:77], v[166:169], v[214:217], v[74:77]
	v_mfma_f32_16x16x32_bf16 v[126:129], v[162:165], v[194:197], v[126:129]
	v_mfma_f32_16x16x32_bf16 v[122:125], v[170:173], v[194:197], v[122:125]
	v_mfma_f32_16x16x32_bf16 v[110:113], v[162:165], v[202:205], v[110:113]
	v_mfma_f32_16x16x32_bf16 v[106:109], v[170:173], v[202:205], v[106:109]
	v_mfma_f32_16x16x32_bf16 v[94:97], v[162:165], v[210:213], v[94:97]
	v_mfma_f32_16x16x32_bf16 v[90:93], v[170:173], v[210:213], v[90:93]
	v_mfma_f32_16x16x32_bf16 v[78:81], v[162:165], v[218:221], v[78:81]
	v_mfma_f32_16x16x32_bf16 v[74:77], v[170:173], v[218:221], v[74:77]
	s_setprio 0
	s_setprio 1
	v_mfma_f32_16x16x32_bf16 v[118:121], v[174:177], v[190:193], v[118:121]
	v_mfma_f32_16x16x32_bf16 v[114:117], v[182:185], v[190:193], v[114:117]
	v_mfma_f32_16x16x32_bf16 v[102:105], v[174:177], v[198:201], v[102:105]
	v_mfma_f32_16x16x32_bf16 v[98:101], v[182:185], v[198:201], v[98:101]
	v_mfma_f32_16x16x32_bf16 v[86:89], v[174:177], v[206:209], v[86:89]
	v_mfma_f32_16x16x32_bf16 v[82:85], v[182:185], v[206:209], v[82:85]
	v_mfma_f32_16x16x32_bf16 v[70:73], v[174:177], v[214:217], v[70:73]
	v_mfma_f32_16x16x32_bf16 v[66:69], v[182:185], v[214:217], v[66:69]
	v_mfma_f32_16x16x32_bf16 v[118:121], v[178:181], v[194:197], v[118:121]
	v_mfma_f32_16x16x32_bf16 v[114:117], v[186:189], v[194:197], v[114:117]
	v_mfma_f32_16x16x32_bf16 v[102:105], v[178:181], v[202:205], v[102:105]
	v_mfma_f32_16x16x32_bf16 v[98:101], v[186:189], v[202:205], v[98:101]
	v_mfma_f32_16x16x32_bf16 v[86:89], v[178:181], v[210:213], v[86:89]
	v_mfma_f32_16x16x32_bf16 v[82:85], v[186:189], v[210:213], v[82:85]
	v_mfma_f32_16x16x32_bf16 v[70:73], v[178:181], v[218:221], v[70:73]
	v_mfma_f32_16x16x32_bf16 v[66:69], v[186:189], v[218:221], v[66:69]
	s_setprio 0
	s_barrier
	s_add_i32 s14, s85, s96
	s_mov_b32 m0, s14
	ds_read_b128 v[190:193], v159 offset:49152
	ds_read_b128 v[194:197], v159 offset:50176
	ds_read_b128 v[198:201], v159 offset:51200
	ds_read_b128 v[202:205], v159 offset:52224
	ds_read_b128 v[206:209], v159 offset:53248
	ds_read_b128 v[210:213], v159 offset:54272
	ds_read_b128 v[214:217], v159 offset:55296
	ds_read_b128 v[218:221], v159 offset:56320
	v_lshl_add_u64 v[152:153], v[152:153], 0, s[22:23]
	global_load_lds_dwordx4 v[152:153], off
	s_add_i32 m0, s14, 0x2000
	s_add_u32 s12, s12, 0x40080
	v_lshl_add_u64 v[152:153], v[222:223], 0, s[22:23]
	s_addc_u32 s13, s13, 0
	s_add_i32 s14, s86, s96
	global_load_lds_dwordx4 v[152:153], off
	v_lshl_add_u64 v[152:153], s[12:13], 0, v[132:133]
	s_mov_b32 m0, s14
	s_nop 0
	global_load_lds_dwordx4 v[152:153], off
	v_lshl_add_u64 v[152:153], s[12:13], 0, v[136:137]
	s_add_i32 m0, s14, 0x2000
	s_nop 0
	global_load_lds_dwordx4 v[152:153], off
	v_lshl_add_u64 v[152:153], v[224:225], 0, s[22:23]
	s_mov_b32 m0, s24
	s_nop 0
	global_load_lds_dwordx4 v[152:153], off
	v_lshl_add_u64 v[152:153], v[226:227], 0, s[22:23]
	s_mov_b32 m0, s25
	s_nop 0
	global_load_lds_dwordx4 v[152:153], off
	s_waitcnt vmcnt(8)
	s_waitcnt lgkmcnt(0)
	s_barrier
	s_setprio 1
	s_waitcnt lgkmcnt(0)
	v_mfma_f32_16x16x32_bf16 v[62:65], v[148:151], v[190:193], v[62:65]
	v_mfma_f32_16x16x32_bf16 v[58:61], v[166:169], v[190:193], v[58:61]
	v_mfma_f32_16x16x32_bf16 v[46:49], v[148:151], v[198:201], v[46:49]
	v_mfma_f32_16x16x32_bf16 v[42:45], v[166:169], v[198:201], v[42:45]
	v_mfma_f32_16x16x32_bf16 v[30:33], v[148:151], v[206:209], v[30:33]
	v_mfma_f32_16x16x32_bf16 v[26:29], v[166:169], v[206:209], v[26:29]
	v_mfma_f32_16x16x32_bf16 v[14:17], v[148:151], v[214:217], v[14:17]
	v_mfma_f32_16x16x32_bf16 v[10:13], v[166:169], v[214:217], v[10:13]
	v_mfma_f32_16x16x32_bf16 v[62:65], v[162:165], v[194:197], v[62:65]
	v_mfma_f32_16x16x32_bf16 v[58:61], v[170:173], v[194:197], v[58:61]
	v_mfma_f32_16x16x32_bf16 v[46:49], v[162:165], v[202:205], v[46:49]
	v_mfma_f32_16x16x32_bf16 v[42:45], v[170:173], v[202:205], v[42:45]
	v_mfma_f32_16x16x32_bf16 v[30:33], v[162:165], v[210:213], v[30:33]
	v_mfma_f32_16x16x32_bf16 v[26:29], v[170:173], v[210:213], v[26:29]
	v_mfma_f32_16x16x32_bf16 v[14:17], v[162:165], v[218:221], v[14:17]
	v_mfma_f32_16x16x32_bf16 v[10:13], v[170:173], v[218:221], v[10:13]
	s_setprio 0
	s_setprio 1
	v_mfma_f32_16x16x32_bf16 v[54:57], v[174:177], v[190:193], v[54:57]
	v_mfma_f32_16x16x32_bf16 v[50:53], v[182:185], v[190:193], v[50:53]
	v_mfma_f32_16x16x32_bf16 v[38:41], v[174:177], v[198:201], v[38:41]
	v_mfma_f32_16x16x32_bf16 v[34:37], v[182:185], v[198:201], v[34:37]
	v_mfma_f32_16x16x32_bf16 v[22:25], v[174:177], v[206:209], v[22:25]
	v_mfma_f32_16x16x32_bf16 v[18:21], v[182:185], v[206:209], v[18:21]
	v_mfma_f32_16x16x32_bf16 v[6:9], v[174:177], v[214:217], v[6:9]
	v_mfma_f32_16x16x32_bf16 v[2:5], v[182:185], v[214:217], v[2:5]
	v_mfma_f32_16x16x32_bf16 v[54:57], v[178:181], v[194:197], v[54:57]
	v_mfma_f32_16x16x32_bf16 v[50:53], v[186:189], v[194:197], v[50:53]
	v_mfma_f32_16x16x32_bf16 v[38:41], v[178:181], v[202:205], v[38:41]
	v_mfma_f32_16x16x32_bf16 v[34:37], v[186:189], v[202:205], v[34:37]
	v_mfma_f32_16x16x32_bf16 v[22:25], v[178:181], v[210:213], v[22:25]
	v_mfma_f32_16x16x32_bf16 v[18:21], v[186:189], v[210:213], v[18:21]
	v_mfma_f32_16x16x32_bf16 v[6:9], v[178:181], v[218:221], v[6:9]
	v_mfma_f32_16x16x32_bf16 v[2:5], v[186:189], v[218:221], v[2:5]
	s_setprio 0
	s_barrier
	s_add_i32 s84, s84, 2
	s_add_u32 s10, s10, 0x100
	s_addc_u32 s11, s11, 0
	s_add_u32 s31, s31, 0x100
	s_addc_u32 s35, s35, 0
	s_cmp_gt_u32 s84, 13
	s_cbranch_scc0 .LBB0_138
	v_readlane_b32 s10, v254, 55
	v_readlane_b32 s11, v254, 56
	s_and_b64 vcc, exec, s[10:11]
	s_cbranch_vccz .LBB0_141
	s_barrier

.LBB0_790:
	s_add_u32 s77, s90, 0xfffc0080
	s_addc_u32 s94, s91, -1
	s_add_i32 vcc_lo, 0, 0x10000
	s_cmp_eq_u32 s12, 12
	s_cselect_b32 s97, s20, s94
	s_cselect_b32 s96, s21, s77
	s_cselect_b32 s95, s23, s27
	s_cselect_b32 s94, s75, s26
	s_add_i32 s77, 0, 0x14000
	v_add_u32_e32 v122, vcc_lo, v229
	v_add_u32_e32 v154, s77, v229
	ds_read_b128 v[90:93], v122
	ds_read_b128 v[102:105], v122 offset:1024
	ds_read_b128 v[114:117], v122 offset:2048
	ds_read_b128 v[122:125], v122 offset:3072
	ds_read_b128 v[130:133], v154
	ds_read_b128 v[142:145], v154 offset:1024
	ds_read_b128 v[146:149], v154 offset:2048
	ds_read_b128 v[154:157], v154 offset:3072
	v_lshl_add_u64 v[210:211], s[90:91], 0, v[198:199]
	s_add_i32 m0, s85, 0xc000
	ds_read_b128 v[162:165], v231
	ds_read_b128 v[166:169], v231 offset:1024
	ds_read_b128 v[170:173], v231 offset:2048
	ds_read_b128 v[174:177], v231 offset:3072
	ds_read_b128 v[178:181], v231 offset:4096
	ds_read_b128 v[182:185], v231 offset:5120
	ds_read_b128 v[202:205], v231 offset:6144
	ds_read_b128 v[206:209], v231 offset:7168
	global_load_lds_dwordx4 v[210:211], off
	v_lshl_add_u64 v[210:211], s[90:91], 0, v[200:201]
	s_add_i32 m0, s85, 0xe000
	s_nop 0
	global_load_lds_dwordx4 v[210:211], off
	s_waitcnt vmcnt(8)
	s_waitcnt lgkmcnt(0)
	s_barrier
	s_setprio 1
	s_waitcnt lgkmcnt(0)
	v_mfma_f32_16x16x32_bf16 v[158:161], v[90:93], v[162:165], v[158:161]
	v_mfma_f32_16x16x32_bf16 v[150:153], v[114:117], v[162:165], v[150:153]
	v_mfma_f32_16x16x32_bf16 v[126:129], v[90:93], v[170:173], v[126:129]
	v_mfma_f32_16x16x32_bf16 v[118:121], v[114:117], v[170:173], v[118:121]
	v_mfma_f32_16x16x32_bf16 v[98:101], v[90:93], v[178:181], v[98:101]
	v_mfma_f32_16x16x32_bf16 v[94:97], v[114:117], v[178:181], v[94:97]
	v_mfma_f32_16x16x32_bf16 v[78:81], v[90:93], v[202:205], v[78:81]
	v_mfma_f32_16x16x32_bf16 v[74:77], v[114:117], v[202:205], v[74:77]
	v_mfma_f32_16x16x32_bf16 v[158:161], v[102:105], v[166:169], v[158:161]
	v_mfma_f32_16x16x32_bf16 v[150:153], v[122:125], v[166:169], v[150:153]
	v_mfma_f32_16x16x32_bf16 v[126:129], v[102:105], v[174:177], v[126:129]
	v_mfma_f32_16x16x32_bf16 v[118:121], v[122:125], v[174:177], v[118:121]
	v_mfma_f32_16x16x32_bf16 v[98:101], v[102:105], v[182:185], v[98:101]
	v_mfma_f32_16x16x32_bf16 v[94:97], v[122:125], v[182:185], v[94:97]
	v_mfma_f32_16x16x32_bf16 v[78:81], v[102:105], v[206:209], v[78:81]
	v_mfma_f32_16x16x32_bf16 v[74:77], v[122:125], v[206:209], v[74:77]
	s_setprio 0
	s_setprio 1
	v_mfma_f32_16x16x32_bf16 v[138:141], v[130:133], v[162:165], v[138:141]
	v_mfma_f32_16x16x32_bf16 v[134:137], v[146:149], v[162:165], v[134:137]
	v_mfma_f32_16x16x32_bf16 v[110:113], v[130:133], v[170:173], v[110:113]
	v_mfma_f32_16x16x32_bf16 v[106:109], v[146:149], v[170:173], v[106:109]
	v_mfma_f32_16x16x32_bf16 v[86:89], v[130:133], v[178:181], v[86:89]
	v_mfma_f32_16x16x32_bf16 v[82:85], v[146:149], v[178:181], v[82:85]
	v_mfma_f32_16x16x32_bf16 v[70:73], v[130:133], v[202:205], v[70:73]
	v_mfma_f32_16x16x32_bf16 v[66:69], v[146:149], v[202:205], v[66:69]
	v_mfma_f32_16x16x32_bf16 v[138:141], v[142:145], v[166:169], v[138:141]
	v_mfma_f32_16x16x32_bf16 v[134:137], v[154:157], v[166:169], v[134:137]
	v_mfma_f32_16x16x32_bf16 v[110:113], v[142:145], v[174:177], v[110:113]
	v_mfma_f32_16x16x32_bf16 v[106:109], v[154:157], v[174:177], v[106:109]
	v_mfma_f32_16x16x32_bf16 v[86:89], v[142:145], v[182:185], v[86:89]
	v_mfma_f32_16x16x32_bf16 v[82:85], v[154:157], v[182:185], v[82:85]
	v_mfma_f32_16x16x32_bf16 v[70:73], v[142:145], v[206:209], v[70:73]
	v_mfma_f32_16x16x32_bf16 v[66:69], v[154:157], v[206:209], v[66:69]
	s_setprio 0
	s_barrier
	s_add_i32 vcc_lo, vcc_lo, s84
	s_mov_b32 m0, vcc_lo
	ds_read_b128 v[162:165], v231 offset:16384
	ds_read_b128 v[166:169], v231 offset:17408
	ds_read_b128 v[170:173], v231 offset:18432
	ds_read_b128 v[174:177], v231 offset:19456
	ds_read_b128 v[178:181], v231 offset:20480
	ds_read_b128 v[182:185], v231 offset:21504
	ds_read_b128 v[202:205], v231 offset:22528
	ds_read_b128 v[206:209], v231 offset:23552
	v_lshl_add_u64 v[210:211], s[94:95], 0, v[186:187]
	global_load_lds_dwordx4 v[210:211], off
	s_add_i32 m0, vcc_lo, 0x2000
	s_add_u32 vcc_lo, s94, 0x40000
	v_lshl_add_u64 v[212:213], s[94:95], 0, v[192:193]
	s_addc_u32 vcc_hi, s95, 0
	s_add_i32 s77, s77, s84
	global_load_lds_dwordx4 v[212:213], off
	v_lshl_add_u64 v[214:215], vcc, 0, v[186:187]
	s_mov_b32 m0, s77
	v_lshl_add_u64 v[216:217], s[96:97], 0, v[194:195]
	global_load_lds_dwordx4 v[214:215], off
	v_lshl_add_u64 v[214:215], vcc, 0, v[192:193]
	s_add_i32 m0, s77, 0x2000
	s_nop 0
	global_load_lds_dwordx4 v[214:215], off
	v_lshl_add_u64 v[214:215], s[96:97], 0, v[196:197]
	s_mov_b32 m0, s85
	s_nop 0
	global_load_lds_dwordx4 v[214:215], off
	s_mov_b32 m0, s86
	s_nop 0
	global_load_lds_dwordx4 v[216:217], off
	s_waitcnt vmcnt(8)
	s_waitcnt lgkmcnt(0)
	s_barrier
	s_setprio 1
	s_waitcnt lgkmcnt(0)
	v_mfma_f32_16x16x32_bf16 v[62:65], v[90:93], v[162:165], v[62:65]
	v_mfma_f32_16x16x32_bf16 v[58:61], v[114:117], v[162:165], v[58:61]
	v_mfma_f32_16x16x32_bf16 v[46:49], v[90:93], v[170:173], v[46:49]
	v_mfma_f32_16x16x32_bf16 v[42:45], v[114:117], v[170:173], v[42:45]
	v_mfma_f32_16x16x32_bf16 v[30:33], v[90:93], v[178:181], v[30:33]
	v_mfma_f32_16x16x32_bf16 v[26:29], v[114:117], v[178:181], v[26:29]
	v_mfma_f32_16x16x32_bf16 v[14:17], v[90:93], v[202:205], v[14:17]
	v_mfma_f32_16x16x32_bf16 v[10:13], v[114:117], v[202:205], v[10:13]
	v_mfma_f32_16x16x32_bf16 v[62:65], v[102:105], v[166:169], v[62:65]
	v_mfma_f32_16x16x32_bf16 v[58:61], v[122:125], v[166:169], v[58:61]
	v_mfma_f32_16x16x32_bf16 v[46:49], v[102:105], v[174:177], v[46:49]
	v_mfma_f32_16x16x32_bf16 v[42:45], v[122:125], v[174:177], v[42:45]
	v_mfma_f32_16x16x32_bf16 v[30:33], v[102:105], v[182:185], v[30:33]
	v_mfma_f32_16x16x32_bf16 v[26:29], v[122:125], v[182:185], v[26:29]
	v_mfma_f32_16x16x32_bf16 v[14:17], v[102:105], v[206:209], v[14:17]
	v_mfma_f32_16x16x32_bf16 v[10:13], v[122:125], v[206:209], v[10:13]
	s_setprio 0
	s_setprio 1
	v_mfma_f32_16x16x32_bf16 v[54:57], v[130:133], v[162:165], v[54:57]
	v_mfma_f32_16x16x32_bf16 v[50:53], v[146:149], v[162:165], v[50:53]
	v_mfma_f32_16x16x32_bf16 v[38:41], v[130:133], v[170:173], v[38:41]
	v_mfma_f32_16x16x32_bf16 v[34:37], v[146:149], v[170:173], v[34:37]
	v_mfma_f32_16x16x32_bf16 v[22:25], v[130:133], v[178:181], v[22:25]
	v_mfma_f32_16x16x32_bf16 v[18:21], v[146:149], v[178:181], v[18:21]
	v_mfma_f32_16x16x32_bf16 v[6:9], v[130:133], v[202:205], v[6:9]
	v_mfma_f32_16x16x32_bf16 v[2:5], v[146:149], v[202:205], v[2:5]
	v_mfma_f32_16x16x32_bf16 v[54:57], v[142:145], v[166:169], v[54:57]
	v_mfma_f32_16x16x32_bf16 v[50:53], v[154:157], v[166:169], v[50:53]
	v_mfma_f32_16x16x32_bf16 v[38:41], v[142:145], v[174:177], v[38:41]
	v_mfma_f32_16x16x32_bf16 v[34:37], v[154:157], v[174:177], v[34:37]
	v_mfma_f32_16x16x32_bf16 v[22:25], v[142:145], v[182:185], v[22:25]
	v_mfma_f32_16x16x32_bf16 v[18:21], v[154:157], v[182:185], v[18:21]
	v_mfma_f32_16x16x32_bf16 v[6:9], v[142:145], v[206:209], v[6:9]
	v_mfma_f32_16x16x32_bf16 v[2:5], v[154:157], v[206:209], v[2:5]
	s_setprio 0
	s_barrier
	s_add_i32 s77, 0, 0x18000
	s_add_i32 vcc_lo, 0, 0x1c000
	v_add_u32_e32 v122, s77, v229
	v_add_u32_e32 v154, vcc_lo, v229
	ds_read_b128 v[90:93], v122
	ds_read_b128 v[102:105], v122 offset:1024
	ds_read_b128 v[114:117], v122 offset:2048
	ds_read_b128 v[122:125], v122 offset:3072
	ds_read_b128 v[130:133], v154
	ds_read_b128 v[142:145], v154 offset:1024
	ds_read_b128 v[146:149], v154 offset:2048
	ds_read_b128 v[154:157], v154 offset:3072
	s_add_u32 s96, s96, 0x40000
	s_addc_u32 s97, s97, 0
	s_mov_b32 m0, s87
	v_lshl_add_u64 v[218:219], s[96:97], 0, v[196:197]
	ds_read_b128 v[162:165], v231 offset:32768
	ds_read_b128 v[166:169], v231 offset:33792
	ds_read_b128 v[170:173], v231 offset:34816
	ds_read_b128 v[174:177], v231 offset:35840
	ds_read_b128 v[178:181], v231 offset:36864
	ds_read_b128 v[182:185], v231 offset:37888
	ds_read_b128 v[202:205], v231 offset:38912
	ds_read_b128 v[206:209], v231 offset:39936
	global_load_lds_dwordx4 v[218:219], off
	v_lshl_add_u64 v[218:219], s[96:97], 0, v[194:195]
	s_mov_b32 m0, s46
	s_nop 0
	global_load_lds_dwordx4 v[218:219], off
	s_waitcnt vmcnt(8)
	s_waitcnt lgkmcnt(0)
	s_barrier
	s_setprio 1
	s_waitcnt lgkmcnt(0)
	v_mfma_f32_16x16x32_bf16 v[158:161], v[90:93], v[162:165], v[158:161]
	v_mfma_f32_16x16x32_bf16 v[150:153], v[114:117], v[162:165], v[150:153]
	v_mfma_f32_16x16x32_bf16 v[126:129], v[90:93], v[170:173], v[126:129]
	v_mfma_f32_16x16x32_bf16 v[118:121], v[114:117], v[170:173], v[118:121]
	v_mfma_f32_16x16x32_bf16 v[98:101], v[90:93], v[178:181], v[98:101]
	v_mfma_f32_16x16x32_bf16 v[94:97], v[114:117], v[178:181], v[94:97]
	v_mfma_f32_16x16x32_bf16 v[78:81], v[90:93], v[202:205], v[78:81]
	v_mfma_f32_16x16x32_bf16 v[74:77], v[114:117], v[202:205], v[74:77]
	v_mfma_f32_16x16x32_bf16 v[158:161], v[102:105], v[166:169], v[158:161]
	v_mfma_f32_16x16x32_bf16 v[150:153], v[122:125], v[166:169], v[150:153]
	v_mfma_f32_16x16x32_bf16 v[126:129], v[102:105], v[174:177], v[126:129]
	v_mfma_f32_16x16x32_bf16 v[118:121], v[122:125], v[174:177], v[118:121]
	v_mfma_f32_16x16x32_bf16 v[98:101], v[102:105], v[182:185], v[98:101]
	v_mfma_f32_16x16x32_bf16 v[94:97], v[122:125], v[182:185], v[94:97]
	v_mfma_f32_16x16x32_bf16 v[78:81], v[102:105], v[206:209], v[78:81]
	v_mfma_f32_16x16x32_bf16 v[74:77], v[122:125], v[206:209], v[74:77]
	s_setprio 0
	s_setprio 1
	v_mfma_f32_16x16x32_bf16 v[138:141], v[130:133], v[162:165], v[138:141]
	v_mfma_f32_16x16x32_bf16 v[134:137], v[146:149], v[162:165], v[134:137]
	v_mfma_f32_16x16x32_bf16 v[110:113], v[130:133], v[170:173], v[110:113]
	v_mfma_f32_16x16x32_bf16 v[106:109], v[146:149], v[170:173], v[106:109]
	v_mfma_f32_16x16x32_bf16 v[86:89], v[130:133], v[178:181], v[86:89]
	v_mfma_f32_16x16x32_bf16 v[82:85], v[146:149], v[178:181], v[82:85]
	v_mfma_f32_16x16x32_bf16 v[70:73], v[130:133], v[202:205], v[70:73]
	v_mfma_f32_16x16x32_bf16 v[66:69], v[146:149], v[202:205], v[66:69]
	v_mfma_f32_16x16x32_bf16 v[138:141], v[142:145], v[166:169], v[138:141]
	v_mfma_f32_16x16x32_bf16 v[134:137], v[154:157], v[166:169], v[134:137]
	v_mfma_f32_16x16x32_bf16 v[110:113], v[142:145], v[174:177], v[110:113]
	v_mfma_f32_16x16x32_bf16 v[106:109], v[154:157], v[174:177], v[106:109]
	v_mfma_f32_16x16x32_bf16 v[86:89], v[142:145], v[182:185], v[86:89]
	v_mfma_f32_16x16x32_bf16 v[82:85], v[154:157], v[182:185], v[82:85]
	v_mfma_f32_16x16x32_bf16 v[70:73], v[142:145], v[206:209], v[70:73]
	v_mfma_f32_16x16x32_bf16 v[66:69], v[154:157], v[206:209], v[66:69]
	s_setprio 0
	s_barrier
	s_add_i32 s77, s77, s84
	s_mov_b32 m0, s77
	ds_read_b128 v[162:165], v231 offset:49152
	ds_read_b128 v[166:169], v231 offset:50176
	ds_read_b128 v[170:173], v231 offset:51200
	ds_read_b128 v[174:177], v231 offset:52224
	ds_read_b128 v[178:181], v231 offset:53248
	ds_read_b128 v[182:185], v231 offset:54272
	ds_read_b128 v[202:205], v231 offset:55296
	ds_read_b128 v[206:209], v231 offset:56320
	v_lshl_add_u64 v[210:211], v[210:211], 0, s[56:57]
	global_load_lds_dwordx4 v[210:211], off
	s_add_i32 m0, s77, 0x2000
	s_add_u32 s94, s94, 0x40080
	v_lshl_add_u64 v[210:211], v[212:213], 0, s[56:57]
	s_addc_u32 s95, s95, 0
	s_add_i32 s77, vcc_lo, s84
	global_load_lds_dwordx4 v[210:211], off
	v_lshl_add_u64 v[210:211], s[94:95], 0, v[186:187]
	s_mov_b32 m0, s77
	s_nop 0
	global_load_lds_dwordx4 v[210:211], off
	v_lshl_add_u64 v[210:211], s[94:95], 0, v[192:193]
	s_add_i32 m0, s77, 0x2000
	s_nop 0
	global_load_lds_dwordx4 v[210:211], off
	v_lshl_add_u64 v[210:211], v[214:215], 0, s[56:57]
	s_mov_b32 m0, s47
	s_nop 0
	global_load_lds_dwordx4 v[210:211], off
	v_lshl_add_u64 v[210:211], v[216:217], 0, s[56:57]
	s_mov_b32 m0, s50
	s_nop 0
	global_load_lds_dwordx4 v[210:211], off
	s_waitcnt vmcnt(8)
	s_waitcnt lgkmcnt(0)
	s_barrier
	s_setprio 1
	s_waitcnt lgkmcnt(0)
	v_mfma_f32_16x16x32_bf16 v[62:65], v[90:93], v[162:165], v[62:65]
	v_mfma_f32_16x16x32_bf16 v[58:61], v[114:117], v[162:165], v[58:61]
	v_mfma_f32_16x16x32_bf16 v[46:49], v[90:93], v[170:173], v[46:49]
	v_mfma_f32_16x16x32_bf16 v[42:45], v[114:117], v[170:173], v[42:45]
	v_mfma_f32_16x16x32_bf16 v[30:33], v[90:93], v[178:181], v[30:33]
	v_mfma_f32_16x16x32_bf16 v[26:29], v[114:117], v[178:181], v[26:29]
	v_mfma_f32_16x16x32_bf16 v[14:17], v[90:93], v[202:205], v[14:17]
	v_mfma_f32_16x16x32_bf16 v[10:13], v[114:117], v[202:205], v[10:13]
	v_mfma_f32_16x16x32_bf16 v[62:65], v[102:105], v[166:169], v[62:65]
	v_mfma_f32_16x16x32_bf16 v[58:61], v[122:125], v[166:169], v[58:61]
	v_mfma_f32_16x16x32_bf16 v[46:49], v[102:105], v[174:177], v[46:49]
	v_mfma_f32_16x16x32_bf16 v[42:45], v[122:125], v[174:177], v[42:45]
	v_mfma_f32_16x16x32_bf16 v[30:33], v[102:105], v[182:185], v[30:33]
	v_mfma_f32_16x16x32_bf16 v[26:29], v[122:125], v[182:185], v[26:29]
	v_mfma_f32_16x16x32_bf16 v[14:17], v[102:105], v[206:209], v[14:17]
	v_mfma_f32_16x16x32_bf16 v[10:13], v[122:125], v[206:209], v[10:13]
	s_setprio 0
	s_setprio 1
	v_mfma_f32_16x16x32_bf16 v[54:57], v[130:133], v[162:165], v[54:57]
	v_mfma_f32_16x16x32_bf16 v[50:53], v[146:149], v[162:165], v[50:53]
	v_mfma_f32_16x16x32_bf16 v[38:41], v[130:133], v[170:173], v[38:41]
	v_mfma_f32_16x16x32_bf16 v[34:37], v[146:149], v[170:173], v[34:37]
	v_mfma_f32_16x16x32_bf16 v[22:25], v[130:133], v[178:181], v[22:25]
	v_mfma_f32_16x16x32_bf16 v[18:21], v[146:149], v[178:181], v[18:21]
	v_mfma_f32_16x16x32_bf16 v[6:9], v[130:133], v[202:205], v[6:9]
	v_mfma_f32_16x16x32_bf16 v[2:5], v[146:149], v[202:205], v[2:5]
	v_mfma_f32_16x16x32_bf16 v[54:57], v[142:145], v[166:169], v[54:57]
	v_mfma_f32_16x16x32_bf16 v[50:53], v[154:157], v[166:169], v[50:53]
	v_mfma_f32_16x16x32_bf16 v[38:41], v[142:145], v[174:177], v[38:41]
	v_mfma_f32_16x16x32_bf16 v[34:37], v[154:157], v[174:177], v[34:37]
	v_mfma_f32_16x16x32_bf16 v[22:25], v[142:145], v[182:185], v[22:25]
	v_mfma_f32_16x16x32_bf16 v[18:21], v[154:157], v[182:185], v[18:21]
	v_mfma_f32_16x16x32_bf16 v[6:9], v[142:145], v[206:209], v[6:9]
	v_mfma_f32_16x16x32_bf16 v[2:5], v[154:157], v[206:209], v[2:5]
	s_setprio 0
	s_barrier
	s_add_i32 s12, s12, 2
	s_add_u32 s90, s90, 0x100
	s_addc_u32 s91, s91, 0
	s_add_u32 s26, s26, 0x100
	s_addc_u32 s27, s27, 0
	s_cmp_gt_u32 s12, 13
	s_cbranch_scc0 .LBB0_790
	s_and_b64 vcc, exec, s[72:73]
	s_cbranch_vccz .LBB0_793
	s_barrier

.LBB0_877:
	ds_read_b128 v[146:149], v163
	ds_read_b128 v[150:153], v163 offset:1024
	ds_read_b128 v[154:157], v163 offset:2048
	ds_read_b128 v[168:171], v163 offset:3072
	ds_read_b128 v[172:175], v164
	ds_read_b128 v[176:179], v164 offset:1024
	ds_read_b128 v[180:183], v164 offset:2048
	ds_read_b128 v[184:187], v164 offset:3072
	s_add_u32 s26, s56, 0xfffc0080
	s_addc_u32 s27, s57, -1
	s_cmp_eq_u32 s12, 12
	s_cselect_b32 s27, s20, s27
	s_cselect_b32 s26, s21, s26
	s_cselect_b32 s73, s37, s55
	s_cselect_b32 s72, s39, s51
	v_lshl_add_u64 v[158:159], s[56:57], 0, v[138:139]
	s_add_i32 m0, s11, 0xc000
	ds_read_b128 v[188:191], v165
	ds_read_b128 v[192:195], v165 offset:1024
	ds_read_b128 v[196:199], v165 offset:2048
	ds_read_b128 v[200:203], v165 offset:3072
	ds_read_b128 v[204:207], v165 offset:4096
	ds_read_b128 v[208:211], v165 offset:5120
	ds_read_b128 v[212:215], v165 offset:6144
	ds_read_b128 v[216:219], v165 offset:7168
	global_load_lds_dwordx4 v[158:159], off
	v_lshl_add_u64 v[158:159], s[56:57], 0, v[140:141]
	s_add_i32 m0, s11, 0xe000
	s_nop 0
	global_load_lds_dwordx4 v[158:159], off
	s_waitcnt vmcnt(8)
	s_waitcnt lgkmcnt(0)
	s_barrier
	s_setprio 1
	s_waitcnt lgkmcnt(0)
	v_mfma_f32_16x16x32_bf16 v[118:121], v[146:149], v[188:191], v[118:121]
	v_mfma_f32_16x16x32_bf16 v[114:117], v[154:157], v[188:191], v[114:117]
	v_mfma_f32_16x16x32_bf16 v[106:109], v[146:149], v[196:199], v[106:109]
	v_mfma_f32_16x16x32_bf16 v[102:105], v[154:157], v[196:199], v[102:105]
	v_mfma_f32_16x16x32_bf16 v[94:97], v[146:149], v[204:207], v[94:97]
	v_mfma_f32_16x16x32_bf16 v[90:93], v[154:157], v[204:207], v[90:93]
	v_mfma_f32_16x16x32_bf16 v[78:81], v[146:149], v[212:215], v[78:81]
	v_mfma_f32_16x16x32_bf16 v[74:77], v[154:157], v[212:215], v[74:77]
	v_mfma_f32_16x16x32_bf16 v[118:121], v[150:153], v[192:195], v[118:121]
	v_mfma_f32_16x16x32_bf16 v[114:117], v[168:171], v[192:195], v[114:117]
	v_mfma_f32_16x16x32_bf16 v[106:109], v[150:153], v[200:203], v[106:109]
	v_mfma_f32_16x16x32_bf16 v[102:105], v[168:171], v[200:203], v[102:105]
	v_mfma_f32_16x16x32_bf16 v[94:97], v[150:153], v[208:211], v[94:97]
	v_mfma_f32_16x16x32_bf16 v[90:93], v[168:171], v[208:211], v[90:93]
	v_mfma_f32_16x16x32_bf16 v[78:81], v[150:153], v[216:219], v[78:81]
	v_mfma_f32_16x16x32_bf16 v[74:77], v[168:171], v[216:219], v[74:77]
	s_setprio 0
	s_setprio 1
	v_mfma_f32_16x16x32_bf16 v[126:129], v[172:175], v[188:191], v[126:129]
	v_mfma_f32_16x16x32_bf16 v[122:125], v[180:183], v[188:191], v[122:125]
	v_mfma_f32_16x16x32_bf16 v[110:113], v[172:175], v[196:199], v[110:113]
	v_mfma_f32_16x16x32_bf16 v[98:101], v[180:183], v[196:199], v[98:101]
	v_mfma_f32_16x16x32_bf16 v[86:89], v[172:175], v[204:207], v[86:89]
	v_mfma_f32_16x16x32_bf16 v[82:85], v[180:183], v[204:207], v[82:85]
	v_mfma_f32_16x16x32_bf16 v[70:73], v[172:175], v[212:215], v[70:73]
	v_mfma_f32_16x16x32_bf16 v[66:69], v[180:183], v[212:215], v[66:69]
	v_mfma_f32_16x16x32_bf16 v[126:129], v[176:179], v[192:195], v[126:129]
	v_mfma_f32_16x16x32_bf16 v[122:125], v[184:187], v[192:195], v[122:125]
	v_mfma_f32_16x16x32_bf16 v[110:113], v[176:179], v[200:203], v[110:113]
	v_mfma_f32_16x16x32_bf16 v[98:101], v[184:187], v[200:203], v[98:101]
	v_mfma_f32_16x16x32_bf16 v[86:89], v[176:179], v[208:211], v[86:89]
	v_mfma_f32_16x16x32_bf16 v[82:85], v[184:187], v[208:211], v[82:85]
	v_mfma_f32_16x16x32_bf16 v[70:73], v[176:179], v[216:219], v[70:73]
	v_mfma_f32_16x16x32_bf16 v[66:69], v[184:187], v[216:219], v[66:69]
	s_setprio 0
	s_barrier
	s_add_i32 s74, s31, s10
	s_mov_b32 m0, s74
	ds_read_b128 v[188:191], v165 offset:16384
	ds_read_b128 v[192:195], v165 offset:17408
	ds_read_b128 v[196:199], v165 offset:18432
	ds_read_b128 v[200:203], v165 offset:19456
	ds_read_b128 v[204:207], v165 offset:20480
	ds_read_b128 v[208:211], v165 offset:21504
	ds_read_b128 v[212:215], v165 offset:22528
	ds_read_b128 v[216:219], v165 offset:23552
	v_lshl_add_u64 v[158:159], s[72:73], 0, v[134:135]
	global_load_lds_dwordx4 v[158:159], off
	s_add_i32 m0, s74, 0x2000
	s_add_u32 s74, s72, 0x40000
	v_lshl_add_u64 v[220:221], s[72:73], 0, v[130:131]
	s_addc_u32 s75, s73, 0
	s_add_i32 s76, s46, s10
	global_load_lds_dwordx4 v[220:221], off
	v_lshl_add_u64 v[228:229], s[74:75], 0, v[134:135]
	s_mov_b32 m0, s76
	v_lshl_add_u64 v[230:231], s[26:27], 0, v[132:133]
	global_load_lds_dwordx4 v[228:229], off
	v_lshl_add_u64 v[228:229], s[74:75], 0, v[130:131]
	s_add_i32 m0, s76, 0x2000
	s_nop 0
	global_load_lds_dwordx4 v[228:229], off
	v_lshl_add_u64 v[228:229], s[26:27], 0, v[136:137]
	s_mov_b32 m0, s11
	s_nop 0
	global_load_lds_dwordx4 v[228:229], off
	s_mov_b32 m0, s13
	s_nop 0
	global_load_lds_dwordx4 v[230:231], off
	s_waitcnt vmcnt(8)
	s_waitcnt lgkmcnt(0)
	s_barrier
	s_setprio 1
	s_waitcnt lgkmcnt(0)
	v_mfma_f32_16x16x32_bf16 v[62:65], v[146:149], v[188:191], v[62:65]
	v_mfma_f32_16x16x32_bf16 v[58:61], v[154:157], v[188:191], v[58:61]
	v_mfma_f32_16x16x32_bf16 v[46:49], v[146:149], v[196:199], v[46:49]
	v_mfma_f32_16x16x32_bf16 v[42:45], v[154:157], v[196:199], v[42:45]
	v_mfma_f32_16x16x32_bf16 v[30:33], v[146:149], v[204:207], v[30:33]
	v_mfma_f32_16x16x32_bf16 v[26:29], v[154:157], v[204:207], v[26:29]
	v_mfma_f32_16x16x32_bf16 v[14:17], v[146:149], v[212:215], v[14:17]
	v_mfma_f32_16x16x32_bf16 v[10:13], v[154:157], v[212:215], v[10:13]
	v_mfma_f32_16x16x32_bf16 v[62:65], v[150:153], v[192:195], v[62:65]
	v_mfma_f32_16x16x32_bf16 v[58:61], v[168:171], v[192:195], v[58:61]
	v_mfma_f32_16x16x32_bf16 v[46:49], v[150:153], v[200:203], v[46:49]
	v_mfma_f32_16x16x32_bf16 v[42:45], v[168:171], v[200:203], v[42:45]
	v_mfma_f32_16x16x32_bf16 v[30:33], v[150:153], v[208:211], v[30:33]
	v_mfma_f32_16x16x32_bf16 v[26:29], v[168:171], v[208:211], v[26:29]
	v_mfma_f32_16x16x32_bf16 v[14:17], v[150:153], v[216:219], v[14:17]
	v_mfma_f32_16x16x32_bf16 v[10:13], v[168:171], v[216:219], v[10:13]
	s_setprio 0
	s_setprio 1
	v_mfma_f32_16x16x32_bf16 v[54:57], v[172:175], v[188:191], v[54:57]
	v_mfma_f32_16x16x32_bf16 v[50:53], v[180:183], v[188:191], v[50:53]
	v_mfma_f32_16x16x32_bf16 v[38:41], v[172:175], v[196:199], v[38:41]
	v_mfma_f32_16x16x32_bf16 v[34:37], v[180:183], v[196:199], v[34:37]
	v_mfma_f32_16x16x32_bf16 v[22:25], v[172:175], v[204:207], v[22:25]
	v_mfma_f32_16x16x32_bf16 v[18:21], v[180:183], v[204:207], v[18:21]
	v_mfma_f32_16x16x32_bf16 v[6:9], v[172:175], v[212:215], v[6:9]
	v_mfma_f32_16x16x32_bf16 v[2:5], v[180:183], v[212:215], v[2:5]
	v_mfma_f32_16x16x32_bf16 v[54:57], v[176:179], v[192:195], v[54:57]
	v_mfma_f32_16x16x32_bf16 v[50:53], v[184:187], v[192:195], v[50:53]
	v_mfma_f32_16x16x32_bf16 v[38:41], v[176:179], v[200:203], v[38:41]
	v_mfma_f32_16x16x32_bf16 v[34:37], v[184:187], v[200:203], v[34:37]
	v_mfma_f32_16x16x32_bf16 v[22:25], v[176:179], v[208:211], v[22:25]
	v_mfma_f32_16x16x32_bf16 v[18:21], v[184:187], v[208:211], v[18:21]
	v_mfma_f32_16x16x32_bf16 v[6:9], v[176:179], v[216:219], v[6:9]
	v_mfma_f32_16x16x32_bf16 v[2:5], v[184:187], v[216:219], v[2:5]
	s_setprio 0
	s_barrier
	s_add_i32 s74, 0, 0x18000
	v_add_u32_e32 v167, s74, v161
	s_add_i32 s75, 0, 0x1c000
	ds_read_b128 v[146:149], v167
	ds_read_b128 v[150:153], v167 offset:1024
	ds_read_b128 v[154:157], v167 offset:2048
	ds_read_b128 v[168:171], v167 offset:3072
	v_add_u32_e32 v167, s75, v161
	ds_read_b128 v[172:175], v167
	ds_read_b128 v[176:179], v167 offset:1024
	ds_read_b128 v[180:183], v167 offset:2048
	ds_read_b128 v[184:187], v167 offset:3072
	s_add_u32 s26, s26, 0x40000
	s_addc_u32 s27, s27, 0
	s_mov_b32 m0, s16
	v_lshl_add_u64 v[232:233], s[26:27], 0, v[136:137]
	ds_read_b128 v[188:191], v165 offset:32768
	ds_read_b128 v[192:195], v165 offset:33792
	ds_read_b128 v[196:199], v165 offset:34816
	ds_read_b128 v[200:203], v165 offset:35840
	ds_read_b128 v[204:207], v165 offset:36864
	ds_read_b128 v[208:211], v165 offset:37888
	ds_read_b128 v[212:215], v165 offset:38912
	ds_read_b128 v[216:219], v165 offset:39936
	global_load_lds_dwordx4 v[232:233], off
	v_lshl_add_u64 v[232:233], s[26:27], 0, v[132:133]
	s_mov_b32 m0, s17
	s_nop 0
	global_load_lds_dwordx4 v[232:233], off
	s_waitcnt vmcnt(8)
	s_waitcnt lgkmcnt(0)
	s_barrier
	s_setprio 1
	s_waitcnt lgkmcnt(0)
	v_mfma_f32_16x16x32_bf16 v[118:121], v[146:149], v[188:191], v[118:121]
	v_mfma_f32_16x16x32_bf16 v[114:117], v[154:157], v[188:191], v[114:117]
	v_mfma_f32_16x16x32_bf16 v[106:109], v[146:149], v[196:199], v[106:109]
	v_mfma_f32_16x16x32_bf16 v[102:105], v[154:157], v[196:199], v[102:105]
	v_mfma_f32_16x16x32_bf16 v[94:97], v[146:149], v[204:207], v[94:97]
	v_mfma_f32_16x16x32_bf16 v[90:93], v[154:157], v[204:207], v[90:93]
	v_mfma_f32_16x16x32_bf16 v[78:81], v[146:149], v[212:215], v[78:81]
	v_mfma_f32_16x16x32_bf16 v[74:77], v[154:157], v[212:215], v[74:77]
	v_mfma_f32_16x16x32_bf16 v[118:121], v[150:153], v[192:195], v[118:121]
	v_mfma_f32_16x16x32_bf16 v[114:117], v[168:171], v[192:195], v[114:117]
	v_mfma_f32_16x16x32_bf16 v[106:109], v[150:153], v[200:203], v[106:109]
	v_mfma_f32_16x16x32_bf16 v[102:105], v[168:171], v[200:203], v[102:105]
	v_mfma_f32_16x16x32_bf16 v[94:97], v[150:153], v[208:211], v[94:97]
	v_mfma_f32_16x16x32_bf16 v[90:93], v[168:171], v[208:211], v[90:93]
	v_mfma_f32_16x16x32_bf16 v[78:81], v[150:153], v[216:219], v[78:81]
	v_mfma_f32_16x16x32_bf16 v[74:77], v[168:171], v[216:219], v[74:77]
	s_setprio 0
	s_setprio 1
	v_mfma_f32_16x16x32_bf16 v[126:129], v[172:175], v[188:191], v[126:129]
	v_mfma_f32_16x16x32_bf16 v[122:125], v[180:183], v[188:191], v[122:125]
	v_mfma_f32_16x16x32_bf16 v[110:113], v[172:175], v[196:199], v[110:113]
	v_mfma_f32_16x16x32_bf16 v[98:101], v[180:183], v[196:199], v[98:101]
	v_mfma_f32_16x16x32_bf16 v[86:89], v[172:175], v[204:207], v[86:89]
	v_mfma_f32_16x16x32_bf16 v[82:85], v[180:183], v[204:207], v[82:85]
	v_mfma_f32_16x16x32_bf16 v[70:73], v[172:175], v[212:215], v[70:73]
	v_mfma_f32_16x16x32_bf16 v[66:69], v[180:183], v[212:215], v[66:69]
	v_mfma_f32_16x16x32_bf16 v[126:129], v[176:179], v[192:195], v[126:129]
	v_mfma_f32_16x16x32_bf16 v[122:125], v[184:187], v[192:195], v[122:125]
	v_mfma_f32_16x16x32_bf16 v[110:113], v[176:179], v[200:203], v[110:113]
	v_mfma_f32_16x16x32_bf16 v[98:101], v[184:187], v[200:203], v[98:101]
	v_mfma_f32_16x16x32_bf16 v[86:89], v[176:179], v[208:211], v[86:89]
	v_mfma_f32_16x16x32_bf16 v[82:85], v[184:187], v[208:211], v[82:85]
	v_mfma_f32_16x16x32_bf16 v[70:73], v[176:179], v[216:219], v[70:73]
	v_mfma_f32_16x16x32_bf16 v[66:69], v[184:187], v[216:219], v[66:69]
	s_setprio 0
	s_barrier
	s_add_i32 s26, s74, s10
	s_mov_b32 m0, s26
	ds_read_b128 v[188:191], v165 offset:49152
	ds_read_b128 v[192:195], v165 offset:50176
	ds_read_b128 v[196:199], v165 offset:51200
	ds_read_b128 v[200:203], v165 offset:52224
	ds_read_b128 v[204:207], v165 offset:53248
	ds_read_b128 v[208:211], v165 offset:54272
	ds_read_b128 v[212:215], v165 offset:55296
	ds_read_b128 v[216:219], v165 offset:56320
	v_lshl_add_u64 v[158:159], v[158:159], 0, s[6:7]
	global_load_lds_dwordx4 v[158:159], off
	s_add_i32 m0, s26, 0x2000
	s_add_u32 s26, s72, 0x40080
	v_lshl_add_u64 v[158:159], v[220:221], 0, s[6:7]
	s_addc_u32 s27, s73, 0
	s_add_i32 s72, s75, s10
	global_load_lds_dwordx4 v[158:159], off
	v_lshl_add_u64 v[158:159], s[26:27], 0, v[134:135]
	s_mov_b32 m0, s72
	s_nop 0
	global_load_lds_dwordx4 v[158:159], off
	v_lshl_add_u64 v[158:159], s[26:27], 0, v[130:131]
	s_add_i32 m0, s72, 0x2000
	s_nop 0
	global_load_lds_dwordx4 v[158:159], off
	v_lshl_add_u64 v[158:159], v[228:229], 0, s[6:7]
	s_mov_b32 m0, s23
	s_nop 0
	global_load_lds_dwordx4 v[158:159], off
	v_lshl_add_u64 v[158:159], v[230:231], 0, s[6:7]
	s_mov_b32 m0, s30
	s_nop 0
	global_load_lds_dwordx4 v[158:159], off
	s_waitcnt vmcnt(8)
	s_waitcnt lgkmcnt(0)
	s_barrier
	s_setprio 1
	s_waitcnt lgkmcnt(0)
	v_mfma_f32_16x16x32_bf16 v[62:65], v[146:149], v[188:191], v[62:65]
	v_mfma_f32_16x16x32_bf16 v[58:61], v[154:157], v[188:191], v[58:61]
	v_mfma_f32_16x16x32_bf16 v[46:49], v[146:149], v[196:199], v[46:49]
	v_mfma_f32_16x16x32_bf16 v[42:45], v[154:157], v[196:199], v[42:45]
	v_mfma_f32_16x16x32_bf16 v[30:33], v[146:149], v[204:207], v[30:33]
	v_mfma_f32_16x16x32_bf16 v[26:29], v[154:157], v[204:207], v[26:29]
	v_mfma_f32_16x16x32_bf16 v[14:17], v[146:149], v[212:215], v[14:17]
	v_mfma_f32_16x16x32_bf16 v[10:13], v[154:157], v[212:215], v[10:13]
	v_mfma_f32_16x16x32_bf16 v[62:65], v[150:153], v[192:195], v[62:65]
	v_mfma_f32_16x16x32_bf16 v[58:61], v[168:171], v[192:195], v[58:61]
	v_mfma_f32_16x16x32_bf16 v[46:49], v[150:153], v[200:203], v[46:49]
	v_mfma_f32_16x16x32_bf16 v[42:45], v[168:171], v[200:203], v[42:45]
	v_mfma_f32_16x16x32_bf16 v[30:33], v[150:153], v[208:211], v[30:33]
	v_mfma_f32_16x16x32_bf16 v[26:29], v[168:171], v[208:211], v[26:29]
	v_mfma_f32_16x16x32_bf16 v[14:17], v[150:153], v[216:219], v[14:17]
	v_mfma_f32_16x16x32_bf16 v[10:13], v[168:171], v[216:219], v[10:13]
	s_setprio 0
	s_setprio 1
	v_mfma_f32_16x16x32_bf16 v[54:57], v[172:175], v[188:191], v[54:57]
	v_mfma_f32_16x16x32_bf16 v[50:53], v[180:183], v[188:191], v[50:53]
	v_mfma_f32_16x16x32_bf16 v[38:41], v[172:175], v[196:199], v[38:41]
	v_mfma_f32_16x16x32_bf16 v[34:37], v[180:183], v[196:199], v[34:37]
	v_mfma_f32_16x16x32_bf16 v[22:25], v[172:175], v[204:207], v[22:25]
	v_mfma_f32_16x16x32_bf16 v[18:21], v[180:183], v[204:207], v[18:21]
	v_mfma_f32_16x16x32_bf16 v[6:9], v[172:175], v[212:215], v[6:9]
	v_mfma_f32_16x16x32_bf16 v[2:5], v[180:183], v[212:215], v[2:5]
	v_mfma_f32_16x16x32_bf16 v[54:57], v[176:179], v[192:195], v[54:57]
	v_mfma_f32_16x16x32_bf16 v[50:53], v[184:187], v[192:195], v[50:53]
	v_mfma_f32_16x16x32_bf16 v[38:41], v[176:179], v[200:203], v[38:41]
	v_mfma_f32_16x16x32_bf16 v[34:37], v[184:187], v[200:203], v[34:37]
	v_mfma_f32_16x16x32_bf16 v[22:25], v[176:179], v[208:211], v[22:25]
	v_mfma_f32_16x16x32_bf16 v[18:21], v[184:187], v[208:211], v[18:21]
	v_mfma_f32_16x16x32_bf16 v[6:9], v[176:179], v[216:219], v[6:9]
	v_mfma_f32_16x16x32_bf16 v[2:5], v[184:187], v[216:219], v[2:5]
	s_setprio 0
	s_barrier
	s_add_i32 s12, s12, 2
	s_add_u32 s56, s56, 0x100
	s_addc_u32 s57, s57, 0
	s_add_u32 s51, s51, 0x100
	s_addc_u32 s55, s55, 0
	s_cmp_gt_u32 s12, 13
	s_cbranch_scc0 .LBB0_877
	s_and_b64 vcc, exec, s[34:35]
	s_cbranch_vccz .LBB0_880
	s_barrier

.LBB0_978:
	s_add_u32 s96, s94, 0x100
	s_addc_u32 s97, s95, 0
	s_add_i32 s15, 0, 0x10000
	s_cmp_eq_u32 s35, 40
	s_cselect_b32 s27, s1, s97
	s_cselect_b32 s26, s0, s96
	s_cselect_b32 vcc_hi, s91, s34
	s_cselect_b32 vcc_lo, s90, s12
	s_add_i32 s68, 0, 0x14000
	v_add_u32_e32 v122, s15, v229
	v_add_u32_e32 v150, s68, v229
	ds_read_b128 v[90:93], v122
	ds_read_b128 v[102:105], v122 offset:1024
	ds_read_b128 v[114:117], v122 offset:2048
	ds_read_b128 v[122:125], v122 offset:3072
	ds_read_b128 v[130:133], v150
	ds_read_b128 v[142:145], v150 offset:1024
	ds_read_b128 v[146:149], v150 offset:2048
	ds_read_b128 v[150:153], v150 offset:3072
	v_lshl_add_u64 v[210:211], s[94:95], 0, v[198:199]
	s_add_i32 m0, s87, 0xc000
	ds_read_b128 v[162:165], v231
	ds_read_b128 v[166:169], v231 offset:1024
	ds_read_b128 v[170:173], v231 offset:2048
	ds_read_b128 v[174:177], v231 offset:3072
	ds_read_b128 v[178:181], v231 offset:4096
	ds_read_b128 v[182:185], v231 offset:5120
	ds_read_b128 v[202:205], v231 offset:6144
	ds_read_b128 v[206:209], v231 offset:7168
	global_load_lds_dwordx4 v[210:211], off
	v_lshl_add_u64 v[210:211], s[94:95], 0, v[200:201]
	s_add_i32 m0, s87, 0xe000
	s_nop 0
	global_load_lds_dwordx4 v[210:211], off
	s_waitcnt vmcnt(8)
	s_waitcnt lgkmcnt(0)
	s_barrier
	s_setprio 1
	s_waitcnt lgkmcnt(0)
	v_mfma_f32_16x16x32_bf16 v[158:161], v[90:93], v[162:165], v[158:161]
	v_mfma_f32_16x16x32_bf16 v[154:157], v[114:117], v[162:165], v[154:157]
	v_mfma_f32_16x16x32_bf16 v[126:129], v[90:93], v[170:173], v[126:129]
	v_mfma_f32_16x16x32_bf16 v[118:121], v[114:117], v[170:173], v[118:121]
	v_mfma_f32_16x16x32_bf16 v[98:101], v[90:93], v[178:181], v[98:101]
	v_mfma_f32_16x16x32_bf16 v[94:97], v[114:117], v[178:181], v[94:97]
	v_mfma_f32_16x16x32_bf16 v[78:81], v[90:93], v[202:205], v[78:81]
	v_mfma_f32_16x16x32_bf16 v[74:77], v[114:117], v[202:205], v[74:77]
	v_mfma_f32_16x16x32_bf16 v[158:161], v[102:105], v[166:169], v[158:161]
	v_mfma_f32_16x16x32_bf16 v[154:157], v[122:125], v[166:169], v[154:157]
	v_mfma_f32_16x16x32_bf16 v[126:129], v[102:105], v[174:177], v[126:129]
	v_mfma_f32_16x16x32_bf16 v[118:121], v[122:125], v[174:177], v[118:121]
	v_mfma_f32_16x16x32_bf16 v[98:101], v[102:105], v[182:185], v[98:101]
	v_mfma_f32_16x16x32_bf16 v[94:97], v[122:125], v[182:185], v[94:97]
	v_mfma_f32_16x16x32_bf16 v[78:81], v[102:105], v[206:209], v[78:81]
	v_mfma_f32_16x16x32_bf16 v[74:77], v[122:125], v[206:209], v[74:77]
	s_setprio 0
	s_setprio 1
	v_mfma_f32_16x16x32_bf16 v[138:141], v[130:133], v[162:165], v[138:141]
	v_mfma_f32_16x16x32_bf16 v[134:137], v[146:149], v[162:165], v[134:137]
	v_mfma_f32_16x16x32_bf16 v[110:113], v[130:133], v[170:173], v[110:113]
	v_mfma_f32_16x16x32_bf16 v[106:109], v[146:149], v[170:173], v[106:109]
	v_mfma_f32_16x16x32_bf16 v[86:89], v[130:133], v[178:181], v[86:89]
	v_mfma_f32_16x16x32_bf16 v[82:85], v[146:149], v[178:181], v[82:85]
	v_mfma_f32_16x16x32_bf16 v[70:73], v[130:133], v[202:205], v[70:73]
	v_mfma_f32_16x16x32_bf16 v[66:69], v[146:149], v[202:205], v[66:69]
	v_mfma_f32_16x16x32_bf16 v[138:141], v[142:145], v[166:169], v[138:141]
	v_mfma_f32_16x16x32_bf16 v[134:137], v[150:153], v[166:169], v[134:137]
	v_mfma_f32_16x16x32_bf16 v[110:113], v[142:145], v[174:177], v[110:113]
	v_mfma_f32_16x16x32_bf16 v[106:109], v[150:153], v[174:177], v[106:109]
	v_mfma_f32_16x16x32_bf16 v[86:89], v[142:145], v[182:185], v[86:89]
	v_mfma_f32_16x16x32_bf16 v[82:85], v[150:153], v[182:185], v[82:85]
	v_mfma_f32_16x16x32_bf16 v[70:73], v[142:145], v[206:209], v[70:73]
	v_mfma_f32_16x16x32_bf16 v[66:69], v[150:153], v[206:209], v[66:69]
	s_setprio 0
	s_barrier
	s_add_i32 s15, s15, s86
	s_mov_b32 m0, s15
	ds_read_b128 v[162:165], v231 offset:16384
	ds_read_b128 v[166:169], v231 offset:17408
	ds_read_b128 v[170:173], v231 offset:18432
	ds_read_b128 v[174:177], v231 offset:19456
	ds_read_b128 v[178:181], v231 offset:20480
	ds_read_b128 v[182:185], v231 offset:21504
	ds_read_b128 v[202:205], v231 offset:22528
	ds_read_b128 v[206:209], v231 offset:23552
	v_lshl_add_u64 v[210:211], vcc, 0, v[186:187]
	global_load_lds_dwordx4 v[210:211], off
	s_add_i32 m0, s15, 0x2000
	s_add_u32 s94, vcc_lo, 0xb0000
	v_lshl_add_u64 v[212:213], vcc, 0, v[192:193]
	s_addc_u32 s95, vcc_hi, 0
	s_add_i32 s15, s68, s86
	global_load_lds_dwordx4 v[212:213], off
	v_lshl_add_u64 v[214:215], s[94:95], 0, v[186:187]
	s_mov_b32 m0, s15
	v_lshl_add_u64 v[216:217], s[26:27], 0, v[194:195]
	global_load_lds_dwordx4 v[214:215], off
	v_lshl_add_u64 v[214:215], s[94:95], 0, v[192:193]
	s_add_i32 m0, s15, 0x2000
	s_nop 0
	global_load_lds_dwordx4 v[214:215], off
	v_lshl_add_u64 v[214:215], s[26:27], 0, v[196:197]
	s_mov_b32 m0, s87
	s_nop 0
	global_load_lds_dwordx4 v[214:215], off
	s_mov_b32 m0, s30
	s_nop 0
	global_load_lds_dwordx4 v[216:217], off
	s_waitcnt vmcnt(8)
	s_waitcnt lgkmcnt(0)
	s_barrier
	s_setprio 1
	s_waitcnt lgkmcnt(0)
	v_mfma_f32_16x16x32_bf16 v[62:65], v[90:93], v[162:165], v[62:65]
	v_mfma_f32_16x16x32_bf16 v[58:61], v[114:117], v[162:165], v[58:61]
	v_mfma_f32_16x16x32_bf16 v[46:49], v[90:93], v[170:173], v[46:49]
	v_mfma_f32_16x16x32_bf16 v[42:45], v[114:117], v[170:173], v[42:45]
	v_mfma_f32_16x16x32_bf16 v[30:33], v[90:93], v[178:181], v[30:33]
	v_mfma_f32_16x16x32_bf16 v[26:29], v[114:117], v[178:181], v[26:29]
	v_mfma_f32_16x16x32_bf16 v[14:17], v[90:93], v[202:205], v[14:17]
	v_mfma_f32_16x16x32_bf16 v[10:13], v[114:117], v[202:205], v[10:13]
	v_mfma_f32_16x16x32_bf16 v[62:65], v[102:105], v[166:169], v[62:65]
	v_mfma_f32_16x16x32_bf16 v[58:61], v[122:125], v[166:169], v[58:61]
	v_mfma_f32_16x16x32_bf16 v[46:49], v[102:105], v[174:177], v[46:49]
	v_mfma_f32_16x16x32_bf16 v[42:45], v[122:125], v[174:177], v[42:45]
	v_mfma_f32_16x16x32_bf16 v[30:33], v[102:105], v[182:185], v[30:33]
	v_mfma_f32_16x16x32_bf16 v[26:29], v[122:125], v[182:185], v[26:29]
	v_mfma_f32_16x16x32_bf16 v[14:17], v[102:105], v[206:209], v[14:17]
	v_mfma_f32_16x16x32_bf16 v[10:13], v[122:125], v[206:209], v[10:13]
	s_setprio 0
	s_setprio 1
	v_mfma_f32_16x16x32_bf16 v[54:57], v[130:133], v[162:165], v[54:57]
	v_mfma_f32_16x16x32_bf16 v[50:53], v[146:149], v[162:165], v[50:53]
	v_mfma_f32_16x16x32_bf16 v[38:41], v[130:133], v[170:173], v[38:41]
	v_mfma_f32_16x16x32_bf16 v[34:37], v[146:149], v[170:173], v[34:37]
	v_mfma_f32_16x16x32_bf16 v[22:25], v[130:133], v[178:181], v[22:25]
	v_mfma_f32_16x16x32_bf16 v[18:21], v[146:149], v[178:181], v[18:21]
	v_mfma_f32_16x16x32_bf16 v[6:9], v[130:133], v[202:205], v[6:9]
	v_mfma_f32_16x16x32_bf16 v[2:5], v[146:149], v[202:205], v[2:5]
	v_mfma_f32_16x16x32_bf16 v[54:57], v[142:145], v[166:169], v[54:57]
	v_mfma_f32_16x16x32_bf16 v[50:53], v[150:153], v[166:169], v[50:53]
	v_mfma_f32_16x16x32_bf16 v[38:41], v[142:145], v[174:177], v[38:41]
	v_mfma_f32_16x16x32_bf16 v[34:37], v[150:153], v[174:177], v[34:37]
	v_mfma_f32_16x16x32_bf16 v[22:25], v[142:145], v[182:185], v[22:25]
	v_mfma_f32_16x16x32_bf16 v[18:21], v[150:153], v[182:185], v[18:21]
	v_mfma_f32_16x16x32_bf16 v[6:9], v[142:145], v[206:209], v[6:9]
	v_mfma_f32_16x16x32_bf16 v[2:5], v[150:153], v[206:209], v[2:5]
	s_setprio 0
	s_barrier
	s_add_i32 s15, 0, 0x18000
	s_add_i32 s68, 0, 0x1c000
	v_add_u32_e32 v122, s15, v229
	v_add_u32_e32 v150, s68, v229
	ds_read_b128 v[90:93], v122
	ds_read_b128 v[102:105], v122 offset:1024
	ds_read_b128 v[114:117], v122 offset:2048
	ds_read_b128 v[122:125], v122 offset:3072
	ds_read_b128 v[130:133], v150
	ds_read_b128 v[142:145], v150 offset:1024
	ds_read_b128 v[146:149], v150 offset:2048
	ds_read_b128 v[150:153], v150 offset:3072
	s_add_u32 s26, s26, 0xb0000
	s_addc_u32 s27, s27, 0
	s_mov_b32 m0, s31
	v_lshl_add_u64 v[218:219], s[26:27], 0, v[196:197]
	ds_read_b128 v[162:165], v231 offset:32768
	ds_read_b128 v[166:169], v231 offset:33792
	ds_read_b128 v[170:173], v231 offset:34816
	ds_read_b128 v[174:177], v231 offset:35840
	ds_read_b128 v[178:181], v231 offset:36864
	ds_read_b128 v[182:185], v231 offset:37888
	ds_read_b128 v[202:205], v231 offset:38912
	ds_read_b128 v[206:209], v231 offset:39936
	global_load_lds_dwordx4 v[218:219], off
	v_lshl_add_u64 v[218:219], s[26:27], 0, v[194:195]
	s_mov_b32 m0, s46
	s_nop 0
	global_load_lds_dwordx4 v[218:219], off
	s_waitcnt vmcnt(8)
	s_waitcnt lgkmcnt(0)
	s_barrier
	s_setprio 1
	s_waitcnt lgkmcnt(0)
	v_mfma_f32_16x16x32_bf16 v[158:161], v[90:93], v[162:165], v[158:161]
	v_mfma_f32_16x16x32_bf16 v[154:157], v[114:117], v[162:165], v[154:157]
	v_mfma_f32_16x16x32_bf16 v[126:129], v[90:93], v[170:173], v[126:129]
	v_mfma_f32_16x16x32_bf16 v[118:121], v[114:117], v[170:173], v[118:121]
	v_mfma_f32_16x16x32_bf16 v[98:101], v[90:93], v[178:181], v[98:101]
	v_mfma_f32_16x16x32_bf16 v[94:97], v[114:117], v[178:181], v[94:97]
	v_mfma_f32_16x16x32_bf16 v[78:81], v[90:93], v[202:205], v[78:81]
	v_mfma_f32_16x16x32_bf16 v[74:77], v[114:117], v[202:205], v[74:77]
	v_mfma_f32_16x16x32_bf16 v[158:161], v[102:105], v[166:169], v[158:161]
	v_mfma_f32_16x16x32_bf16 v[154:157], v[122:125], v[166:169], v[154:157]
	v_mfma_f32_16x16x32_bf16 v[126:129], v[102:105], v[174:177], v[126:129]
	v_mfma_f32_16x16x32_bf16 v[118:121], v[122:125], v[174:177], v[118:121]
	v_mfma_f32_16x16x32_bf16 v[98:101], v[102:105], v[182:185], v[98:101]
	v_mfma_f32_16x16x32_bf16 v[94:97], v[122:125], v[182:185], v[94:97]
	v_mfma_f32_16x16x32_bf16 v[78:81], v[102:105], v[206:209], v[78:81]
	v_mfma_f32_16x16x32_bf16 v[74:77], v[122:125], v[206:209], v[74:77]
	s_setprio 0
	s_setprio 1
	v_mfma_f32_16x16x32_bf16 v[138:141], v[130:133], v[162:165], v[138:141]
	v_mfma_f32_16x16x32_bf16 v[134:137], v[146:149], v[162:165], v[134:137]
	v_mfma_f32_16x16x32_bf16 v[110:113], v[130:133], v[170:173], v[110:113]
	v_mfma_f32_16x16x32_bf16 v[106:109], v[146:149], v[170:173], v[106:109]
	v_mfma_f32_16x16x32_bf16 v[86:89], v[130:133], v[178:181], v[86:89]
	v_mfma_f32_16x16x32_bf16 v[82:85], v[146:149], v[178:181], v[82:85]
	v_mfma_f32_16x16x32_bf16 v[70:73], v[130:133], v[202:205], v[70:73]
	v_mfma_f32_16x16x32_bf16 v[66:69], v[146:149], v[202:205], v[66:69]
	v_mfma_f32_16x16x32_bf16 v[138:141], v[142:145], v[166:169], v[138:141]
	v_mfma_f32_16x16x32_bf16 v[134:137], v[150:153], v[166:169], v[134:137]
	v_mfma_f32_16x16x32_bf16 v[110:113], v[142:145], v[174:177], v[110:113]
	v_mfma_f32_16x16x32_bf16 v[106:109], v[150:153], v[174:177], v[106:109]
	v_mfma_f32_16x16x32_bf16 v[86:89], v[142:145], v[182:185], v[86:89]
	v_mfma_f32_16x16x32_bf16 v[82:85], v[150:153], v[182:185], v[82:85]
	v_mfma_f32_16x16x32_bf16 v[70:73], v[142:145], v[206:209], v[70:73]
	v_mfma_f32_16x16x32_bf16 v[66:69], v[150:153], v[206:209], v[66:69]
	s_setprio 0
	s_barrier
	s_add_i32 s15, s15, s86
	s_mov_b32 m0, s15
	ds_read_b128 v[162:165], v231 offset:49152
	ds_read_b128 v[166:169], v231 offset:50176
	ds_read_b128 v[170:173], v231 offset:51200
	ds_read_b128 v[174:177], v231 offset:52224
	ds_read_b128 v[178:181], v231 offset:53248
	ds_read_b128 v[182:185], v231 offset:54272
	ds_read_b128 v[202:205], v231 offset:55296
	ds_read_b128 v[206:209], v231 offset:56320
	v_lshl_add_u64 v[210:211], v[210:211], 0, s[76:77]
	global_load_lds_dwordx4 v[210:211], off
	s_add_i32 m0, s15, 0x2000
	s_add_u32 s26, vcc_lo, 0xb0080
	v_lshl_add_u64 v[210:211], v[212:213], 0, s[76:77]
	s_addc_u32 s27, vcc_hi, 0
	s_add_i32 s15, s68, s86
	global_load_lds_dwordx4 v[210:211], off
	v_lshl_add_u64 v[210:211], s[26:27], 0, v[186:187]
	s_mov_b32 m0, s15
	s_nop 0
	global_load_lds_dwordx4 v[210:211], off
	v_lshl_add_u64 v[210:211], s[26:27], 0, v[192:193]
	s_add_i32 m0, s15, 0x2000
	s_nop 0
	global_load_lds_dwordx4 v[210:211], off
	v_lshl_add_u64 v[210:211], v[214:215], 0, s[76:77]
	s_mov_b32 m0, s47
	s_nop 0
	global_load_lds_dwordx4 v[210:211], off
	v_lshl_add_u64 v[210:211], v[216:217], 0, s[76:77]
	s_mov_b32 m0, s22
	s_nop 0
	global_load_lds_dwordx4 v[210:211], off
	s_waitcnt vmcnt(8)
	s_waitcnt lgkmcnt(0)
	s_barrier
	s_setprio 1
	s_waitcnt lgkmcnt(0)
	v_mfma_f32_16x16x32_bf16 v[62:65], v[90:93], v[162:165], v[62:65]
	v_mfma_f32_16x16x32_bf16 v[58:61], v[114:117], v[162:165], v[58:61]
	v_mfma_f32_16x16x32_bf16 v[46:49], v[90:93], v[170:173], v[46:49]
	v_mfma_f32_16x16x32_bf16 v[42:45], v[114:117], v[170:173], v[42:45]
	v_mfma_f32_16x16x32_bf16 v[30:33], v[90:93], v[178:181], v[30:33]
	v_mfma_f32_16x16x32_bf16 v[26:29], v[114:117], v[178:181], v[26:29]
	v_mfma_f32_16x16x32_bf16 v[14:17], v[90:93], v[202:205], v[14:17]
	v_mfma_f32_16x16x32_bf16 v[10:13], v[114:117], v[202:205], v[10:13]
	v_mfma_f32_16x16x32_bf16 v[62:65], v[102:105], v[166:169], v[62:65]
	v_mfma_f32_16x16x32_bf16 v[58:61], v[122:125], v[166:169], v[58:61]
	v_mfma_f32_16x16x32_bf16 v[46:49], v[102:105], v[174:177], v[46:49]
	v_mfma_f32_16x16x32_bf16 v[42:45], v[122:125], v[174:177], v[42:45]
	v_mfma_f32_16x16x32_bf16 v[30:33], v[102:105], v[182:185], v[30:33]
	v_mfma_f32_16x16x32_bf16 v[26:29], v[122:125], v[182:185], v[26:29]
	v_mfma_f32_16x16x32_bf16 v[14:17], v[102:105], v[206:209], v[14:17]
	v_mfma_f32_16x16x32_bf16 v[10:13], v[122:125], v[206:209], v[10:13]
	s_setprio 0
	s_setprio 1
	v_mfma_f32_16x16x32_bf16 v[54:57], v[130:133], v[162:165], v[54:57]
	v_mfma_f32_16x16x32_bf16 v[50:53], v[146:149], v[162:165], v[50:53]
	v_mfma_f32_16x16x32_bf16 v[38:41], v[130:133], v[170:173], v[38:41]
	v_mfma_f32_16x16x32_bf16 v[34:37], v[146:149], v[170:173], v[34:37]
	v_mfma_f32_16x16x32_bf16 v[22:25], v[130:133], v[178:181], v[22:25]
	v_mfma_f32_16x16x32_bf16 v[18:21], v[146:149], v[178:181], v[18:21]
	v_mfma_f32_16x16x32_bf16 v[6:9], v[130:133], v[202:205], v[6:9]
	v_mfma_f32_16x16x32_bf16 v[2:5], v[146:149], v[202:205], v[2:5]
	v_mfma_f32_16x16x32_bf16 v[54:57], v[142:145], v[166:169], v[54:57]
	v_mfma_f32_16x16x32_bf16 v[50:53], v[150:153], v[166:169], v[50:53]
	v_mfma_f32_16x16x32_bf16 v[38:41], v[142:145], v[174:177], v[38:41]
	v_mfma_f32_16x16x32_bf16 v[34:37], v[150:153], v[174:177], v[34:37]
	v_mfma_f32_16x16x32_bf16 v[22:25], v[142:145], v[182:185], v[22:25]
	v_mfma_f32_16x16x32_bf16 v[18:21], v[150:153], v[182:185], v[18:21]
	v_mfma_f32_16x16x32_bf16 v[6:9], v[142:145], v[206:209], v[6:9]
	v_mfma_f32_16x16x32_bf16 v[2:5], v[150:153], v[206:209], v[2:5]
	s_setprio 0
	s_barrier
	s_add_i32 s35, s35, 2
	s_add_u32 s12, s12, 0x100
	s_addc_u32 s34, s34, 0
	s_cmp_gt_u32 s35, 41
	s_mov_b64 s[94:95], s[96:97]
	s_cbranch_scc0 .LBB0_978
	s_and_b64 vcc, exec, s[88:89]
	s_cbranch_vccz .LBB0_981
	s_barrier

.LBB0_1167:
	s_add_u32 s15, s82, 0xfffc0080
	s_addc_u32 s34, s83, -1
	s_add_i32 s35, 0, 0x10000
	s_cmp_eq_u32 s12, 12
	s_cselect_b32 s91, s20, s34
	s_cselect_b32 s90, s21, s15
	s_cselect_b32 s89, s22, s31
	s_cselect_b32 s88, s23, s30
	s_add_i32 s15, 0, 0x14000
	v_add_u32_e32 v78, s35, v212
	v_add_u32_e32 v130, s15, v212
	ds_read_b128 v[66:69], v78
	ds_read_b128 v[70:73], v78 offset:1024
	ds_read_b128 v[74:77], v78 offset:2048
	ds_read_b128 v[78:81], v78 offset:3072
	ds_read_b128 v[86:89], v130
	ds_read_b128 v[102:105], v130 offset:1024
	ds_read_b128 v[110:113], v130 offset:2048
	ds_read_b128 v[130:133], v130 offset:3072
	v_lshl_add_u64 v[216:217], s[82:83], 0, v[186:187]
	s_add_i32 m0, s65, 0xc000
	ds_read_b128 v[158:161], v214
	ds_read_b128 v[166:169], v214 offset:1024
	ds_read_b128 v[170:173], v214 offset:2048
	ds_read_b128 v[190:193], v214 offset:3072
	ds_read_b128 v[194:197], v214 offset:4096
	ds_read_b128 v[198:201], v214 offset:5120
	ds_read_b128 v[202:205], v214 offset:6144
	ds_read_b128 v[206:209], v214 offset:7168
	global_load_lds_dwordx4 v[216:217], off
	v_lshl_add_u64 v[216:217], s[82:83], 0, v[188:189]
	s_add_i32 m0, s65, 0xe000
	s_nop 0
	global_load_lds_dwordx4 v[216:217], off
	s_waitcnt vmcnt(8)
	s_waitcnt lgkmcnt(0)
	s_barrier
	s_setprio 1
	s_waitcnt lgkmcnt(0)
	v_mfma_f32_16x16x32_bf16 v[162:165], v[66:69], v[158:161], v[162:165]
	v_mfma_f32_16x16x32_bf16 v[150:153], v[74:77], v[158:161], v[150:153]
	v_mfma_f32_16x16x32_bf16 v[142:145], v[66:69], v[170:173], v[142:145]
	v_mfma_f32_16x16x32_bf16 v[134:137], v[74:77], v[170:173], v[134:137]
	v_mfma_f32_16x16x32_bf16 v[122:125], v[66:69], v[194:197], v[122:125]
	v_mfma_f32_16x16x32_bf16 v[114:117], v[74:77], v[194:197], v[114:117]
	v_mfma_f32_16x16x32_bf16 v[98:101], v[66:69], v[202:205], v[98:101]
	v_mfma_f32_16x16x32_bf16 v[90:93], v[74:77], v[202:205], v[90:93]
	v_mfma_f32_16x16x32_bf16 v[162:165], v[70:73], v[166:169], v[162:165]
	v_mfma_f32_16x16x32_bf16 v[150:153], v[78:81], v[166:169], v[150:153]
	v_mfma_f32_16x16x32_bf16 v[142:145], v[70:73], v[190:193], v[142:145]
	v_mfma_f32_16x16x32_bf16 v[134:137], v[78:81], v[190:193], v[134:137]
	v_mfma_f32_16x16x32_bf16 v[122:125], v[70:73], v[198:201], v[122:125]
	v_mfma_f32_16x16x32_bf16 v[114:117], v[78:81], v[198:201], v[114:117]
	v_mfma_f32_16x16x32_bf16 v[98:101], v[70:73], v[206:209], v[98:101]
	v_mfma_f32_16x16x32_bf16 v[90:93], v[78:81], v[206:209], v[90:93]
	s_setprio 0
	s_setprio 1
	v_mfma_f32_16x16x32_bf16 v[154:157], v[86:89], v[158:161], v[154:157]
	v_mfma_f32_16x16x32_bf16 v[146:149], v[110:113], v[158:161], v[146:149]
	v_mfma_f32_16x16x32_bf16 v[138:141], v[86:89], v[170:173], v[138:141]
	v_mfma_f32_16x16x32_bf16 v[126:129], v[110:113], v[170:173], v[126:129]
	v_mfma_f32_16x16x32_bf16 v[118:121], v[86:89], v[194:197], v[118:121]
	v_mfma_f32_16x16x32_bf16 v[106:109], v[110:113], v[194:197], v[106:109]
	v_mfma_f32_16x16x32_bf16 v[94:97], v[86:89], v[202:205], v[94:97]
	v_mfma_f32_16x16x32_bf16 v[82:85], v[110:113], v[202:205], v[82:85]
	v_mfma_f32_16x16x32_bf16 v[154:157], v[102:105], v[166:169], v[154:157]
	v_mfma_f32_16x16x32_bf16 v[146:149], v[130:133], v[166:169], v[146:149]
	v_mfma_f32_16x16x32_bf16 v[138:141], v[102:105], v[190:193], v[138:141]
	v_mfma_f32_16x16x32_bf16 v[126:129], v[130:133], v[190:193], v[126:129]
	v_mfma_f32_16x16x32_bf16 v[118:121], v[102:105], v[198:201], v[118:121]
	v_mfma_f32_16x16x32_bf16 v[106:109], v[130:133], v[198:201], v[106:109]
	v_mfma_f32_16x16x32_bf16 v[94:97], v[102:105], v[206:209], v[94:97]
	v_mfma_f32_16x16x32_bf16 v[82:85], v[130:133], v[206:209], v[82:85]
	s_setprio 0
	s_barrier
	s_add_i32 s34, s35, s47
	s_mov_b32 m0, s34
	ds_read_b128 v[158:161], v214 offset:16384
	ds_read_b128 v[166:169], v214 offset:17408
	ds_read_b128 v[170:173], v214 offset:18432
	ds_read_b128 v[190:193], v214 offset:19456
	ds_read_b128 v[194:197], v214 offset:20480
	ds_read_b128 v[198:201], v214 offset:21504
	ds_read_b128 v[202:205], v214 offset:22528
	ds_read_b128 v[206:209], v214 offset:23552
	v_lshl_add_u64 v[216:217], s[88:89], 0, v[174:175]
	global_load_lds_dwordx4 v[216:217], off
	s_add_i32 m0, s34, 0x2000
	s_add_u32 s34, s88, 0x40000
	v_lshl_add_u64 v[218:219], s[88:89], 0, v[180:181]
	s_addc_u32 s35, s89, 0
	s_add_i32 s15, s15, s47
	global_load_lds_dwordx4 v[218:219], off
	v_lshl_add_u64 v[220:221], s[34:35], 0, v[174:175]
	s_mov_b32 m0, s15
	v_lshl_add_u64 v[228:229], s[90:91], 0, v[182:183]
	global_load_lds_dwordx4 v[220:221], off
	v_lshl_add_u64 v[220:221], s[34:35], 0, v[180:181]
	s_add_i32 m0, s15, 0x2000
	s_nop 0
	global_load_lds_dwordx4 v[220:221], off
	v_lshl_add_u64 v[220:221], s[90:91], 0, v[184:185]
	s_mov_b32 m0, s65
	s_nop 0
	global_load_lds_dwordx4 v[220:221], off
	s_mov_b32 m0, s84
	s_nop 0
	global_load_lds_dwordx4 v[228:229], off
	s_waitcnt vmcnt(8)
	s_waitcnt lgkmcnt(0)
	s_barrier
	s_setprio 1
	s_waitcnt lgkmcnt(0)
	v_mfma_f32_16x16x32_bf16 v[62:65], v[66:69], v[158:161], v[62:65]
	v_mfma_f32_16x16x32_bf16 v[54:57], v[74:77], v[158:161], v[54:57]
	v_mfma_f32_16x16x32_bf16 v[46:49], v[66:69], v[170:173], v[46:49]
	v_mfma_f32_16x16x32_bf16 v[38:41], v[74:77], v[170:173], v[38:41]
	v_mfma_f32_16x16x32_bf16 v[30:33], v[66:69], v[194:197], v[30:33]
	v_mfma_f32_16x16x32_bf16 v[22:25], v[74:77], v[194:197], v[22:25]
	v_mfma_f32_16x16x32_bf16 v[14:17], v[66:69], v[202:205], v[14:17]
	v_mfma_f32_16x16x32_bf16 v[6:9], v[74:77], v[202:205], v[6:9]
	v_mfma_f32_16x16x32_bf16 v[62:65], v[70:73], v[166:169], v[62:65]
	v_mfma_f32_16x16x32_bf16 v[54:57], v[78:81], v[166:169], v[54:57]
	v_mfma_f32_16x16x32_bf16 v[46:49], v[70:73], v[190:193], v[46:49]
	v_mfma_f32_16x16x32_bf16 v[38:41], v[78:81], v[190:193], v[38:41]
	v_mfma_f32_16x16x32_bf16 v[30:33], v[70:73], v[198:201], v[30:33]
	v_mfma_f32_16x16x32_bf16 v[22:25], v[78:81], v[198:201], v[22:25]
	v_mfma_f32_16x16x32_bf16 v[14:17], v[70:73], v[206:209], v[14:17]
	v_mfma_f32_16x16x32_bf16 v[6:9], v[78:81], v[206:209], v[6:9]
	s_setprio 0
	s_setprio 1
	v_mfma_f32_16x16x32_bf16 v[58:61], v[86:89], v[158:161], v[58:61]
	v_mfma_f32_16x16x32_bf16 v[50:53], v[110:113], v[158:161], v[50:53]
	v_mfma_f32_16x16x32_bf16 v[42:45], v[86:89], v[170:173], v[42:45]
	v_mfma_f32_16x16x32_bf16 v[34:37], v[110:113], v[170:173], v[34:37]
	v_mfma_f32_16x16x32_bf16 v[26:29], v[86:89], v[194:197], v[26:29]
	v_mfma_f32_16x16x32_bf16 v[18:21], v[110:113], v[194:197], v[18:21]
	v_mfma_f32_16x16x32_bf16 v[10:13], v[86:89], v[202:205], v[10:13]
	v_mfma_f32_16x16x32_bf16 v[2:5], v[110:113], v[202:205], v[2:5]
	v_mfma_f32_16x16x32_bf16 v[58:61], v[102:105], v[166:169], v[58:61]
	v_mfma_f32_16x16x32_bf16 v[50:53], v[130:133], v[166:169], v[50:53]
	v_mfma_f32_16x16x32_bf16 v[42:45], v[102:105], v[190:193], v[42:45]
	v_mfma_f32_16x16x32_bf16 v[34:37], v[130:133], v[190:193], v[34:37]
	v_mfma_f32_16x16x32_bf16 v[26:29], v[102:105], v[198:201], v[26:29]
	v_mfma_f32_16x16x32_bf16 v[18:21], v[130:133], v[198:201], v[18:21]
	v_mfma_f32_16x16x32_bf16 v[10:13], v[102:105], v[206:209], v[10:13]
	v_mfma_f32_16x16x32_bf16 v[2:5], v[130:133], v[206:209], v[2:5]
	s_setprio 0
	s_barrier
	s_add_i32 s15, 0, 0x18000
	s_add_i32 s75, 0, 0x1c000
	v_add_u32_e32 v78, s15, v212
	v_add_u32_e32 v130, s75, v212
	ds_read_b128 v[66:69], v78
	ds_read_b128 v[70:73], v78 offset:1024
	ds_read_b128 v[74:77], v78 offset:2048
	ds_read_b128 v[78:81], v78 offset:3072
	ds_read_b128 v[86:89], v130
	ds_read_b128 v[102:105], v130 offset:1024
	ds_read_b128 v[110:113], v130 offset:2048
	ds_read_b128 v[130:133], v130 offset:3072
	s_add_u32 s34, s90, 0x40000
	s_addc_u32 s35, s91, 0
	s_mov_b32 m0, s85
	v_lshl_add_u64 v[230:231], s[34:35], 0, v[184:185]
	ds_read_b128 v[158:161], v214 offset:32768
	ds_read_b128 v[166:169], v214 offset:33792
	ds_read_b128 v[170:173], v214 offset:34816
	ds_read_b128 v[190:193], v214 offset:35840
	ds_read_b128 v[194:197], v214 offset:36864
	ds_read_b128 v[198:201], v214 offset:37888
	ds_read_b128 v[202:205], v214 offset:38912
	ds_read_b128 v[206:209], v214 offset:39936
	global_load_lds_dwordx4 v[230:231], off
	v_lshl_add_u64 v[230:231], s[34:35], 0, v[182:183]
	s_mov_b32 m0, s86
	s_nop 0
	global_load_lds_dwordx4 v[230:231], off
	s_waitcnt vmcnt(8)
	s_waitcnt lgkmcnt(0)
	s_barrier
	s_setprio 1
	s_waitcnt lgkmcnt(0)
	v_mfma_f32_16x16x32_bf16 v[162:165], v[66:69], v[158:161], v[162:165]
	v_mfma_f32_16x16x32_bf16 v[150:153], v[74:77], v[158:161], v[150:153]
	v_mfma_f32_16x16x32_bf16 v[142:145], v[66:69], v[170:173], v[142:145]
	v_mfma_f32_16x16x32_bf16 v[134:137], v[74:77], v[170:173], v[134:137]
	v_mfma_f32_16x16x32_bf16 v[122:125], v[66:69], v[194:197], v[122:125]
	v_mfma_f32_16x16x32_bf16 v[114:117], v[74:77], v[194:197], v[114:117]
	v_mfma_f32_16x16x32_bf16 v[98:101], v[66:69], v[202:205], v[98:101]
	v_mfma_f32_16x16x32_bf16 v[90:93], v[74:77], v[202:205], v[90:93]
	v_mfma_f32_16x16x32_bf16 v[162:165], v[70:73], v[166:169], v[162:165]
	v_mfma_f32_16x16x32_bf16 v[150:153], v[78:81], v[166:169], v[150:153]
	v_mfma_f32_16x16x32_bf16 v[142:145], v[70:73], v[190:193], v[142:145]
	v_mfma_f32_16x16x32_bf16 v[134:137], v[78:81], v[190:193], v[134:137]
	v_mfma_f32_16x16x32_bf16 v[122:125], v[70:73], v[198:201], v[122:125]
	v_mfma_f32_16x16x32_bf16 v[114:117], v[78:81], v[198:201], v[114:117]
	v_mfma_f32_16x16x32_bf16 v[98:101], v[70:73], v[206:209], v[98:101]
	v_mfma_f32_16x16x32_bf16 v[90:93], v[78:81], v[206:209], v[90:93]
	s_setprio 0
	s_setprio 1
	v_mfma_f32_16x16x32_bf16 v[154:157], v[86:89], v[158:161], v[154:157]
	v_mfma_f32_16x16x32_bf16 v[146:149], v[110:113], v[158:161], v[146:149]
	v_mfma_f32_16x16x32_bf16 v[138:141], v[86:89], v[170:173], v[138:141]
	v_mfma_f32_16x16x32_bf16 v[126:129], v[110:113], v[170:173], v[126:129]
	v_mfma_f32_16x16x32_bf16 v[118:121], v[86:89], v[194:197], v[118:121]
	v_mfma_f32_16x16x32_bf16 v[106:109], v[110:113], v[194:197], v[106:109]
	v_mfma_f32_16x16x32_bf16 v[94:97], v[86:89], v[202:205], v[94:97]
	v_mfma_f32_16x16x32_bf16 v[82:85], v[110:113], v[202:205], v[82:85]
	v_mfma_f32_16x16x32_bf16 v[154:157], v[102:105], v[166:169], v[154:157]
	v_mfma_f32_16x16x32_bf16 v[146:149], v[130:133], v[166:169], v[146:149]
	v_mfma_f32_16x16x32_bf16 v[138:141], v[102:105], v[190:193], v[138:141]
	v_mfma_f32_16x16x32_bf16 v[126:129], v[130:133], v[190:193], v[126:129]
	v_mfma_f32_16x16x32_bf16 v[118:121], v[102:105], v[198:201], v[118:121]
	v_mfma_f32_16x16x32_bf16 v[106:109], v[130:133], v[198:201], v[106:109]
	v_mfma_f32_16x16x32_bf16 v[94:97], v[102:105], v[206:209], v[94:97]
	v_mfma_f32_16x16x32_bf16 v[82:85], v[130:133], v[206:209], v[82:85]
	s_setprio 0
	s_barrier
	s_add_i32 s15, s15, s47
	s_mov_b32 m0, s15
	ds_read_b128 v[158:161], v214 offset:49152
	ds_read_b128 v[166:169], v214 offset:50176
	ds_read_b128 v[170:173], v214 offset:51200
	ds_read_b128 v[190:193], v214 offset:52224
	ds_read_b128 v[194:197], v214 offset:53248
	ds_read_b128 v[198:201], v214 offset:54272
	ds_read_b128 v[202:205], v214 offset:55296
	ds_read_b128 v[206:209], v214 offset:56320
	v_lshl_add_u64 v[216:217], v[216:217], 0, s[68:69]
	global_load_lds_dwordx4 v[216:217], off
	s_add_i32 m0, s15, 0x2000
	s_add_u32 s34, s88, 0x40080
	v_lshl_add_u64 v[216:217], v[218:219], 0, s[68:69]
	s_addc_u32 s35, s89, 0
	s_add_i32 s15, s75, s47
	global_load_lds_dwordx4 v[216:217], off
	v_lshl_add_u64 v[216:217], s[34:35], 0, v[174:175]
	s_mov_b32 m0, s15
	s_nop 0
	global_load_lds_dwordx4 v[216:217], off
	v_lshl_add_u64 v[216:217], s[34:35], 0, v[180:181]
	s_add_i32 m0, s15, 0x2000
	s_nop 0
	global_load_lds_dwordx4 v[216:217], off
	v_lshl_add_u64 v[216:217], v[220:221], 0, s[68:69]
	s_mov_b32 m0, s87
	s_nop 0
	global_load_lds_dwordx4 v[216:217], off
	v_lshl_add_u64 v[216:217], v[228:229], 0, s[68:69]
	s_mov_b32 m0, s94
	s_nop 0
	global_load_lds_dwordx4 v[216:217], off
	s_waitcnt vmcnt(8)
	s_waitcnt lgkmcnt(0)
	s_barrier
	s_setprio 1
	s_waitcnt lgkmcnt(0)
	v_mfma_f32_16x16x32_bf16 v[62:65], v[66:69], v[158:161], v[62:65]
	v_mfma_f32_16x16x32_bf16 v[54:57], v[74:77], v[158:161], v[54:57]
	v_mfma_f32_16x16x32_bf16 v[46:49], v[66:69], v[170:173], v[46:49]
	v_mfma_f32_16x16x32_bf16 v[38:41], v[74:77], v[170:173], v[38:41]
	v_mfma_f32_16x16x32_bf16 v[30:33], v[66:69], v[194:197], v[30:33]
	v_mfma_f32_16x16x32_bf16 v[22:25], v[74:77], v[194:197], v[22:25]
	v_mfma_f32_16x16x32_bf16 v[14:17], v[66:69], v[202:205], v[14:17]
	v_mfma_f32_16x16x32_bf16 v[6:9], v[74:77], v[202:205], v[6:9]
	v_mfma_f32_16x16x32_bf16 v[62:65], v[70:73], v[166:169], v[62:65]
	v_mfma_f32_16x16x32_bf16 v[54:57], v[78:81], v[166:169], v[54:57]
	v_mfma_f32_16x16x32_bf16 v[46:49], v[70:73], v[190:193], v[46:49]
	v_mfma_f32_16x16x32_bf16 v[38:41], v[78:81], v[190:193], v[38:41]
	v_mfma_f32_16x16x32_bf16 v[30:33], v[70:73], v[198:201], v[30:33]
	v_mfma_f32_16x16x32_bf16 v[22:25], v[78:81], v[198:201], v[22:25]
	v_mfma_f32_16x16x32_bf16 v[14:17], v[70:73], v[206:209], v[14:17]
	v_mfma_f32_16x16x32_bf16 v[6:9], v[78:81], v[206:209], v[6:9]
	s_setprio 0
	s_setprio 1
	v_mfma_f32_16x16x32_bf16 v[58:61], v[86:89], v[158:161], v[58:61]
	v_mfma_f32_16x16x32_bf16 v[50:53], v[110:113], v[158:161], v[50:53]
	v_mfma_f32_16x16x32_bf16 v[42:45], v[86:89], v[170:173], v[42:45]
	v_mfma_f32_16x16x32_bf16 v[34:37], v[110:113], v[170:173], v[34:37]
	v_mfma_f32_16x16x32_bf16 v[26:29], v[86:89], v[194:197], v[26:29]
	v_mfma_f32_16x16x32_bf16 v[18:21], v[110:113], v[194:197], v[18:21]
	v_mfma_f32_16x16x32_bf16 v[10:13], v[86:89], v[202:205], v[10:13]
	v_mfma_f32_16x16x32_bf16 v[2:5], v[110:113], v[202:205], v[2:5]
	v_mfma_f32_16x16x32_bf16 v[58:61], v[102:105], v[166:169], v[58:61]
	v_mfma_f32_16x16x32_bf16 v[50:53], v[130:133], v[166:169], v[50:53]
	v_mfma_f32_16x16x32_bf16 v[42:45], v[102:105], v[190:193], v[42:45]
	v_mfma_f32_16x16x32_bf16 v[34:37], v[130:133], v[190:193], v[34:37]
	v_mfma_f32_16x16x32_bf16 v[26:29], v[102:105], v[198:201], v[26:29]
	v_mfma_f32_16x16x32_bf16 v[18:21], v[130:133], v[198:201], v[18:21]
	v_mfma_f32_16x16x32_bf16 v[10:13], v[102:105], v[206:209], v[10:13]
	v_mfma_f32_16x16x32_bf16 v[2:5], v[130:133], v[206:209], v[2:5]
	s_setprio 0
	s_barrier
	s_add_i32 s12, s12, 2
	s_add_u32 s82, s82, 0x100
	s_addc_u32 s83, s83, 0
	s_add_u32 s30, s30, 0x100
	s_addc_u32 s31, s31, 0
	s_cmp_gt_u32 s12, 13
	s_cbranch_scc0 .LBB0_1167
	s_and_b64 vcc, exec, s[72:73]
	s_cbranch_vccz .LBB0_1170
	s_barrier

.LBB0_1258:
	ds_read_b128 v[146:149], v163
	ds_read_b128 v[150:153], v163 offset:1024
	ds_read_b128 v[154:157], v163 offset:2048
	ds_read_b128 v[168:171], v163 offset:3072
	ds_read_b128 v[172:175], v164
	ds_read_b128 v[176:179], v164 offset:1024
	ds_read_b128 v[180:183], v164 offset:2048
	ds_read_b128 v[184:187], v164 offset:3072
	s_add_u32 s15, s48, 0xfffc0080
	s_addc_u32 s34, s49, -1
	s_cmp_eq_u32 s12, 12
	s_cselect_b32 s53, s20, s34
	s_cselect_b32 s52, s21, s15
	s_cselect_b32 s51, s29, s57
	s_cselect_b32 s50, s31, s56
	v_lshl_add_u64 v[158:159], s[48:49], 0, v[138:139]
	s_add_i32 m0, s11, 0xc000
	ds_read_b128 v[188:191], v165
	ds_read_b128 v[192:195], v165 offset:1024
	ds_read_b128 v[196:199], v165 offset:2048
	ds_read_b128 v[200:203], v165 offset:3072
	ds_read_b128 v[204:207], v165 offset:4096
	ds_read_b128 v[208:211], v165 offset:5120
	ds_read_b128 v[212:215], v165 offset:6144
	ds_read_b128 v[216:219], v165 offset:7168
	global_load_lds_dwordx4 v[158:159], off
	v_lshl_add_u64 v[158:159], s[48:49], 0, v[140:141]
	s_add_i32 m0, s11, 0xe000
	s_nop 0
	global_load_lds_dwordx4 v[158:159], off
	s_waitcnt vmcnt(8)
	s_waitcnt lgkmcnt(0)
	s_barrier
	s_setprio 1
	s_waitcnt lgkmcnt(0)
	v_mfma_f32_16x16x32_bf16 v[118:121], v[146:149], v[188:191], v[118:121]
	v_mfma_f32_16x16x32_bf16 v[114:117], v[154:157], v[188:191], v[114:117]
	v_mfma_f32_16x16x32_bf16 v[106:109], v[146:149], v[196:199], v[106:109]
	v_mfma_f32_16x16x32_bf16 v[102:105], v[154:157], v[196:199], v[102:105]
	v_mfma_f32_16x16x32_bf16 v[94:97], v[146:149], v[204:207], v[94:97]
	v_mfma_f32_16x16x32_bf16 v[90:93], v[154:157], v[204:207], v[90:93]
	v_mfma_f32_16x16x32_bf16 v[78:81], v[146:149], v[212:215], v[78:81]
	v_mfma_f32_16x16x32_bf16 v[74:77], v[154:157], v[212:215], v[74:77]
	v_mfma_f32_16x16x32_bf16 v[118:121], v[150:153], v[192:195], v[118:121]
	v_mfma_f32_16x16x32_bf16 v[114:117], v[168:171], v[192:195], v[114:117]
	v_mfma_f32_16x16x32_bf16 v[106:109], v[150:153], v[200:203], v[106:109]
	v_mfma_f32_16x16x32_bf16 v[102:105], v[168:171], v[200:203], v[102:105]
	v_mfma_f32_16x16x32_bf16 v[94:97], v[150:153], v[208:211], v[94:97]
	v_mfma_f32_16x16x32_bf16 v[90:93], v[168:171], v[208:211], v[90:93]
	v_mfma_f32_16x16x32_bf16 v[78:81], v[150:153], v[216:219], v[78:81]
	v_mfma_f32_16x16x32_bf16 v[74:77], v[168:171], v[216:219], v[74:77]
	s_setprio 0
	s_setprio 1
	v_mfma_f32_16x16x32_bf16 v[126:129], v[172:175], v[188:191], v[126:129]
	v_mfma_f32_16x16x32_bf16 v[122:125], v[180:183], v[188:191], v[122:125]
	v_mfma_f32_16x16x32_bf16 v[110:113], v[172:175], v[196:199], v[110:113]
	v_mfma_f32_16x16x32_bf16 v[98:101], v[180:183], v[196:199], v[98:101]
	v_mfma_f32_16x16x32_bf16 v[86:89], v[172:175], v[204:207], v[86:89]
	v_mfma_f32_16x16x32_bf16 v[82:85], v[180:183], v[204:207], v[82:85]
	v_mfma_f32_16x16x32_bf16 v[70:73], v[172:175], v[212:215], v[70:73]
	v_mfma_f32_16x16x32_bf16 v[66:69], v[180:183], v[212:215], v[66:69]
	v_mfma_f32_16x16x32_bf16 v[126:129], v[176:179], v[192:195], v[126:129]
	v_mfma_f32_16x16x32_bf16 v[122:125], v[184:187], v[192:195], v[122:125]
	v_mfma_f32_16x16x32_bf16 v[110:113], v[176:179], v[200:203], v[110:113]
	v_mfma_f32_16x16x32_bf16 v[98:101], v[184:187], v[200:203], v[98:101]
	v_mfma_f32_16x16x32_bf16 v[86:89], v[176:179], v[208:211], v[86:89]
	v_mfma_f32_16x16x32_bf16 v[82:85], v[184:187], v[208:211], v[82:85]
	v_mfma_f32_16x16x32_bf16 v[70:73], v[176:179], v[216:219], v[70:73]
	v_mfma_f32_16x16x32_bf16 v[66:69], v[184:187], v[216:219], v[66:69]
	s_setprio 0
	s_barrier
	s_add_i32 s15, s37, s10
	s_mov_b32 m0, s15
	ds_read_b128 v[188:191], v165 offset:16384
	ds_read_b128 v[192:195], v165 offset:17408
	ds_read_b128 v[196:199], v165 offset:18432
	ds_read_b128 v[200:203], v165 offset:19456
	ds_read_b128 v[204:207], v165 offset:20480
	ds_read_b128 v[208:211], v165 offset:21504
	ds_read_b128 v[212:215], v165 offset:22528
	ds_read_b128 v[216:219], v165 offset:23552
	v_lshl_add_u64 v[158:159], s[50:51], 0, v[132:133]
	global_load_lds_dwordx4 v[158:159], off
	s_add_i32 m0, s15, 0x2000
	s_add_u32 s34, s50, 0x40000
	v_lshl_add_u64 v[220:221], s[50:51], 0, v[136:137]
	s_addc_u32 s35, s51, 0
	s_add_i32 s15, s47, s10
	global_load_lds_dwordx4 v[220:221], off
	v_lshl_add_u64 v[228:229], s[34:35], 0, v[132:133]
	s_mov_b32 m0, s15
	v_lshl_add_u64 v[230:231], s[52:53], 0, v[134:135]
	global_load_lds_dwordx4 v[228:229], off
	v_lshl_add_u64 v[228:229], s[34:35], 0, v[136:137]
	s_add_i32 m0, s15, 0x2000
	s_nop 0
	global_load_lds_dwordx4 v[228:229], off
	v_lshl_add_u64 v[228:229], s[52:53], 0, v[130:131]
	s_mov_b32 m0, s11
	s_nop 0
	global_load_lds_dwordx4 v[228:229], off
	s_mov_b32 m0, s13
	s_nop 0
	global_load_lds_dwordx4 v[230:231], off
	s_waitcnt vmcnt(8)
	s_waitcnt lgkmcnt(0)
	s_barrier
	s_setprio 1
	s_waitcnt lgkmcnt(0)
	v_mfma_f32_16x16x32_bf16 v[62:65], v[146:149], v[188:191], v[62:65]
	v_mfma_f32_16x16x32_bf16 v[58:61], v[154:157], v[188:191], v[58:61]
	v_mfma_f32_16x16x32_bf16 v[46:49], v[146:149], v[196:199], v[46:49]
	v_mfma_f32_16x16x32_bf16 v[42:45], v[154:157], v[196:199], v[42:45]
	v_mfma_f32_16x16x32_bf16 v[30:33], v[146:149], v[204:207], v[30:33]
	v_mfma_f32_16x16x32_bf16 v[26:29], v[154:157], v[204:207], v[26:29]
	v_mfma_f32_16x16x32_bf16 v[14:17], v[146:149], v[212:215], v[14:17]
	v_mfma_f32_16x16x32_bf16 v[10:13], v[154:157], v[212:215], v[10:13]
	v_mfma_f32_16x16x32_bf16 v[62:65], v[150:153], v[192:195], v[62:65]
	v_mfma_f32_16x16x32_bf16 v[58:61], v[168:171], v[192:195], v[58:61]
	v_mfma_f32_16x16x32_bf16 v[46:49], v[150:153], v[200:203], v[46:49]
	v_mfma_f32_16x16x32_bf16 v[42:45], v[168:171], v[200:203], v[42:45]
	v_mfma_f32_16x16x32_bf16 v[30:33], v[150:153], v[208:211], v[30:33]
	v_mfma_f32_16x16x32_bf16 v[26:29], v[168:171], v[208:211], v[26:29]
	v_mfma_f32_16x16x32_bf16 v[14:17], v[150:153], v[216:219], v[14:17]
	v_mfma_f32_16x16x32_bf16 v[10:13], v[168:171], v[216:219], v[10:13]
	s_setprio 0
	s_setprio 1
	v_mfma_f32_16x16x32_bf16 v[54:57], v[172:175], v[188:191], v[54:57]
	v_mfma_f32_16x16x32_bf16 v[50:53], v[180:183], v[188:191], v[50:53]
	v_mfma_f32_16x16x32_bf16 v[38:41], v[172:175], v[196:199], v[38:41]
	v_mfma_f32_16x16x32_bf16 v[34:37], v[180:183], v[196:199], v[34:37]
	v_mfma_f32_16x16x32_bf16 v[22:25], v[172:175], v[204:207], v[22:25]
	v_mfma_f32_16x16x32_bf16 v[18:21], v[180:183], v[204:207], v[18:21]
	v_mfma_f32_16x16x32_bf16 v[6:9], v[172:175], v[212:215], v[6:9]
	v_mfma_f32_16x16x32_bf16 v[2:5], v[180:183], v[212:215], v[2:5]
	v_mfma_f32_16x16x32_bf16 v[54:57], v[176:179], v[192:195], v[54:57]
	v_mfma_f32_16x16x32_bf16 v[50:53], v[184:187], v[192:195], v[50:53]
	v_mfma_f32_16x16x32_bf16 v[38:41], v[176:179], v[200:203], v[38:41]
	v_mfma_f32_16x16x32_bf16 v[34:37], v[184:187], v[200:203], v[34:37]
	v_mfma_f32_16x16x32_bf16 v[22:25], v[176:179], v[208:211], v[22:25]
	v_mfma_f32_16x16x32_bf16 v[18:21], v[184:187], v[208:211], v[18:21]
	v_mfma_f32_16x16x32_bf16 v[6:9], v[176:179], v[216:219], v[6:9]
	v_mfma_f32_16x16x32_bf16 v[2:5], v[184:187], v[216:219], v[2:5]
	s_setprio 0
	s_barrier
	s_add_i32 s15, 0, 0x18000
	v_add_u32_e32 v167, s15, v161
	s_add_i32 s58, 0, 0x1c000
	ds_read_b128 v[146:149], v167
	ds_read_b128 v[150:153], v167 offset:1024
	ds_read_b128 v[154:157], v167 offset:2048
	ds_read_b128 v[168:171], v167 offset:3072
	v_add_u32_e32 v167, s58, v161
	ds_read_b128 v[172:175], v167
	ds_read_b128 v[176:179], v167 offset:1024
	ds_read_b128 v[180:183], v167 offset:2048
	ds_read_b128 v[184:187], v167 offset:3072
	s_add_u32 s34, s52, 0x40000
	s_addc_u32 s35, s53, 0
	s_mov_b32 m0, s16
	v_lshl_add_u64 v[232:233], s[34:35], 0, v[130:131]
	ds_read_b128 v[188:191], v165 offset:32768
	ds_read_b128 v[192:195], v165 offset:33792
	ds_read_b128 v[196:199], v165 offset:34816
	ds_read_b128 v[200:203], v165 offset:35840
	ds_read_b128 v[204:207], v165 offset:36864
	ds_read_b128 v[208:211], v165 offset:37888
	ds_read_b128 v[212:215], v165 offset:38912
	ds_read_b128 v[216:219], v165 offset:39936
	global_load_lds_dwordx4 v[232:233], off
	v_lshl_add_u64 v[232:233], s[34:35], 0, v[134:135]
	s_mov_b32 m0, s17
	s_nop 0
	global_load_lds_dwordx4 v[232:233], off
	s_waitcnt vmcnt(8)
	s_waitcnt lgkmcnt(0)
	s_barrier
	s_setprio 1
	s_waitcnt lgkmcnt(0)
	v_mfma_f32_16x16x32_bf16 v[118:121], v[146:149], v[188:191], v[118:121]
	v_mfma_f32_16x16x32_bf16 v[114:117], v[154:157], v[188:191], v[114:117]
	v_mfma_f32_16x16x32_bf16 v[106:109], v[146:149], v[196:199], v[106:109]
	v_mfma_f32_16x16x32_bf16 v[102:105], v[154:157], v[196:199], v[102:105]
	v_mfma_f32_16x16x32_bf16 v[94:97], v[146:149], v[204:207], v[94:97]
	v_mfma_f32_16x16x32_bf16 v[90:93], v[154:157], v[204:207], v[90:93]
	v_mfma_f32_16x16x32_bf16 v[78:81], v[146:149], v[212:215], v[78:81]
	v_mfma_f32_16x16x32_bf16 v[74:77], v[154:157], v[212:215], v[74:77]
	v_mfma_f32_16x16x32_bf16 v[118:121], v[150:153], v[192:195], v[118:121]
	v_mfma_f32_16x16x32_bf16 v[114:117], v[168:171], v[192:195], v[114:117]
	v_mfma_f32_16x16x32_bf16 v[106:109], v[150:153], v[200:203], v[106:109]
	v_mfma_f32_16x16x32_bf16 v[102:105], v[168:171], v[200:203], v[102:105]
	v_mfma_f32_16x16x32_bf16 v[94:97], v[150:153], v[208:211], v[94:97]
	v_mfma_f32_16x16x32_bf16 v[90:93], v[168:171], v[208:211], v[90:93]
	v_mfma_f32_16x16x32_bf16 v[78:81], v[150:153], v[216:219], v[78:81]
	v_mfma_f32_16x16x32_bf16 v[74:77], v[168:171], v[216:219], v[74:77]
	s_setprio 0
	s_setprio 1
	v_mfma_f32_16x16x32_bf16 v[126:129], v[172:175], v[188:191], v[126:129]
	v_mfma_f32_16x16x32_bf16 v[122:125], v[180:183], v[188:191], v[122:125]
	v_mfma_f32_16x16x32_bf16 v[110:113], v[172:175], v[196:199], v[110:113]
	v_mfma_f32_16x16x32_bf16 v[98:101], v[180:183], v[196:199], v[98:101]
	v_mfma_f32_16x16x32_bf16 v[86:89], v[172:175], v[204:207], v[86:89]
	v_mfma_f32_16x16x32_bf16 v[82:85], v[180:183], v[204:207], v[82:85]
	v_mfma_f32_16x16x32_bf16 v[70:73], v[172:175], v[212:215], v[70:73]
	v_mfma_f32_16x16x32_bf16 v[66:69], v[180:183], v[212:215], v[66:69]
	v_mfma_f32_16x16x32_bf16 v[126:129], v[176:179], v[192:195], v[126:129]
	v_mfma_f32_16x16x32_bf16 v[122:125], v[184:187], v[192:195], v[122:125]
	v_mfma_f32_16x16x32_bf16 v[110:113], v[176:179], v[200:203], v[110:113]
	v_mfma_f32_16x16x32_bf16 v[98:101], v[184:187], v[200:203], v[98:101]
	v_mfma_f32_16x16x32_bf16 v[86:89], v[176:179], v[208:211], v[86:89]
	v_mfma_f32_16x16x32_bf16 v[82:85], v[184:187], v[208:211], v[82:85]
	v_mfma_f32_16x16x32_bf16 v[70:73], v[176:179], v[216:219], v[70:73]
	v_mfma_f32_16x16x32_bf16 v[66:69], v[184:187], v[216:219], v[66:69]
	s_setprio 0
	s_barrier
	s_add_i32 s15, s15, s10
	s_mov_b32 m0, s15
	ds_read_b128 v[188:191], v165 offset:49152
	ds_read_b128 v[192:195], v165 offset:50176
	ds_read_b128 v[196:199], v165 offset:51200
	ds_read_b128 v[200:203], v165 offset:52224
	ds_read_b128 v[204:207], v165 offset:53248
	ds_read_b128 v[208:211], v165 offset:54272
	ds_read_b128 v[212:215], v165 offset:55296
	ds_read_b128 v[216:219], v165 offset:56320
	v_lshl_add_u64 v[158:159], v[158:159], 0, s[6:7]
	global_load_lds_dwordx4 v[158:159], off
	s_add_i32 m0, s15, 0x2000
	s_add_u32 s34, s50, 0x40080
	v_lshl_add_u64 v[158:159], v[220:221], 0, s[6:7]
	s_addc_u32 s35, s51, 0
	s_add_i32 s15, s58, s10
	global_load_lds_dwordx4 v[158:159], off
	v_lshl_add_u64 v[158:159], s[34:35], 0, v[132:133]
	s_mov_b32 m0, s15
	s_nop 0
	global_load_lds_dwordx4 v[158:159], off
	v_lshl_add_u64 v[158:159], s[34:35], 0, v[136:137]
	s_add_i32 m0, s15, 0x2000
	s_nop 0
	global_load_lds_dwordx4 v[158:159], off
	v_lshl_add_u64 v[158:159], v[228:229], 0, s[6:7]
	s_mov_b32 m0, s23
	s_nop 0
	global_load_lds_dwordx4 v[158:159], off
	v_lshl_add_u64 v[158:159], v[230:231], 0, s[6:7]
	s_mov_b32 m0, s36
	s_nop 0
	global_load_lds_dwordx4 v[158:159], off
	s_waitcnt vmcnt(8)
	s_waitcnt lgkmcnt(0)
	s_barrier
	s_setprio 1
	s_waitcnt lgkmcnt(0)
	v_mfma_f32_16x16x32_bf16 v[62:65], v[146:149], v[188:191], v[62:65]
	v_mfma_f32_16x16x32_bf16 v[58:61], v[154:157], v[188:191], v[58:61]
	v_mfma_f32_16x16x32_bf16 v[46:49], v[146:149], v[196:199], v[46:49]
	v_mfma_f32_16x16x32_bf16 v[42:45], v[154:157], v[196:199], v[42:45]
	v_mfma_f32_16x16x32_bf16 v[30:33], v[146:149], v[204:207], v[30:33]
	v_mfma_f32_16x16x32_bf16 v[26:29], v[154:157], v[204:207], v[26:29]
	v_mfma_f32_16x16x32_bf16 v[14:17], v[146:149], v[212:215], v[14:17]
	v_mfma_f32_16x16x32_bf16 v[10:13], v[154:157], v[212:215], v[10:13]
	v_mfma_f32_16x16x32_bf16 v[62:65], v[150:153], v[192:195], v[62:65]
	v_mfma_f32_16x16x32_bf16 v[58:61], v[168:171], v[192:195], v[58:61]
	v_mfma_f32_16x16x32_bf16 v[46:49], v[150:153], v[200:203], v[46:49]
	v_mfma_f32_16x16x32_bf16 v[42:45], v[168:171], v[200:203], v[42:45]
	v_mfma_f32_16x16x32_bf16 v[30:33], v[150:153], v[208:211], v[30:33]
	v_mfma_f32_16x16x32_bf16 v[26:29], v[168:171], v[208:211], v[26:29]
	v_mfma_f32_16x16x32_bf16 v[14:17], v[150:153], v[216:219], v[14:17]
	v_mfma_f32_16x16x32_bf16 v[10:13], v[168:171], v[216:219], v[10:13]
	s_setprio 0
	s_setprio 1
	v_mfma_f32_16x16x32_bf16 v[54:57], v[172:175], v[188:191], v[54:57]
	v_mfma_f32_16x16x32_bf16 v[50:53], v[180:183], v[188:191], v[50:53]
	v_mfma_f32_16x16x32_bf16 v[38:41], v[172:175], v[196:199], v[38:41]
	v_mfma_f32_16x16x32_bf16 v[34:37], v[180:183], v[196:199], v[34:37]
	v_mfma_f32_16x16x32_bf16 v[22:25], v[172:175], v[204:207], v[22:25]
	v_mfma_f32_16x16x32_bf16 v[18:21], v[180:183], v[204:207], v[18:21]
	v_mfma_f32_16x16x32_bf16 v[6:9], v[172:175], v[212:215], v[6:9]
	v_mfma_f32_16x16x32_bf16 v[2:5], v[180:183], v[212:215], v[2:5]
	v_mfma_f32_16x16x32_bf16 v[54:57], v[176:179], v[192:195], v[54:57]
	v_mfma_f32_16x16x32_bf16 v[50:53], v[184:187], v[192:195], v[50:53]
	v_mfma_f32_16x16x32_bf16 v[38:41], v[176:179], v[200:203], v[38:41]
	v_mfma_f32_16x16x32_bf16 v[34:37], v[184:187], v[200:203], v[34:37]
	v_mfma_f32_16x16x32_bf16 v[22:25], v[176:179], v[208:211], v[22:25]
	v_mfma_f32_16x16x32_bf16 v[18:21], v[184:187], v[208:211], v[18:21]
	v_mfma_f32_16x16x32_bf16 v[6:9], v[176:179], v[216:219], v[6:9]
	v_mfma_f32_16x16x32_bf16 v[2:5], v[184:187], v[216:219], v[2:5]
	s_setprio 0
	s_barrier
	s_add_i32 s12, s12, 2
	s_add_u32 s48, s48, 0x100
	s_addc_u32 s49, s49, 0
	s_add_u32 s56, s56, 0x100
	s_addc_u32 s57, s57, 0
	s_cmp_gt_u32 s12, 13
	s_cbranch_scc0 .LBB0_1258
	s_and_b64 vcc, exec, s[8:9]
	s_cbranch_vccz .LBB0_1261
	s_barrier

.LBB0_1341:
	ds_read_b128 v[106:109], v217
	ds_read_b128 v[110:113], v217 offset:1024
	ds_read_b128 v[126:129], v217 offset:2048
	ds_read_b128 v[138:141], v217 offset:3072
	ds_read_b128 v[146:149], v218
	ds_read_b128 v[150:153], v218 offset:1024
	ds_read_b128 v[154:157], v218 offset:2048
	ds_read_b128 v[158:161], v218 offset:3072
	s_add_u32 s48, s46, 0x100
	s_addc_u32 s49, s47, 0
	s_cmp_eq_u32 s63, 40
	s_cselect_b32 s53, s1, s49
	s_cselect_b32 s52, s0, s48
	s_cselect_b32 s51, s41, s62
	s_cselect_b32 s50, s40, s12
	v_lshl_add_u64 v[210:211], s[46:47], 0, v[194:195]
	s_add_i32 m0, s11, 0xc000
	ds_read_b128 v[162:165], v219
	ds_read_b128 v[166:169], v219 offset:1024
	ds_read_b128 v[170:173], v219 offset:2048
	ds_read_b128 v[174:177], v219 offset:3072
	ds_read_b128 v[178:181], v219 offset:4096
	ds_read_b128 v[182:185], v219 offset:5120
	ds_read_b128 v[202:205], v219 offset:6144
	ds_read_b128 v[206:209], v219 offset:7168
	global_load_lds_dwordx4 v[210:211], off
	v_lshl_add_u64 v[210:211], s[46:47], 0, v[196:197]
	s_add_i32 m0, s11, 0xe000
	s_nop 0
	global_load_lds_dwordx4 v[210:211], off
	s_waitcnt vmcnt(8)
	s_waitcnt lgkmcnt(0)
	s_barrier
	s_setprio 1
	s_waitcnt lgkmcnt(0)
	v_mfma_f32_16x16x32_bf16 v[142:145], v[106:109], v[162:165], v[142:145]
	v_mfma_f32_16x16x32_bf16 v[134:137], v[126:129], v[162:165], v[134:137]
	v_mfma_f32_16x16x32_bf16 v[118:121], v[106:109], v[170:173], v[118:121]
	v_mfma_f32_16x16x32_bf16 v[114:117], v[126:129], v[170:173], v[114:117]
	v_mfma_f32_16x16x32_bf16 v[94:97], v[106:109], v[178:181], v[94:97]
	v_mfma_f32_16x16x32_bf16 v[90:93], v[126:129], v[178:181], v[90:93]
	v_mfma_f32_16x16x32_bf16 v[78:81], v[106:109], v[202:205], v[78:81]
	v_mfma_f32_16x16x32_bf16 v[74:77], v[126:129], v[202:205], v[74:77]
	v_mfma_f32_16x16x32_bf16 v[142:145], v[110:113], v[166:169], v[142:145]
	v_mfma_f32_16x16x32_bf16 v[134:137], v[138:141], v[166:169], v[134:137]
	v_mfma_f32_16x16x32_bf16 v[118:121], v[110:113], v[174:177], v[118:121]
	v_mfma_f32_16x16x32_bf16 v[114:117], v[138:141], v[174:177], v[114:117]
	v_mfma_f32_16x16x32_bf16 v[94:97], v[110:113], v[182:185], v[94:97]
	v_mfma_f32_16x16x32_bf16 v[90:93], v[138:141], v[182:185], v[90:93]
	v_mfma_f32_16x16x32_bf16 v[78:81], v[110:113], v[206:209], v[78:81]
	v_mfma_f32_16x16x32_bf16 v[74:77], v[138:141], v[206:209], v[74:77]
	s_setprio 0
	s_setprio 1
	v_mfma_f32_16x16x32_bf16 v[130:133], v[146:149], v[162:165], v[130:133]
	v_mfma_f32_16x16x32_bf16 v[122:125], v[154:157], v[162:165], v[122:125]
	v_mfma_f32_16x16x32_bf16 v[102:105], v[146:149], v[170:173], v[102:105]
	v_mfma_f32_16x16x32_bf16 v[98:101], v[154:157], v[170:173], v[98:101]
	v_mfma_f32_16x16x32_bf16 v[86:89], v[146:149], v[178:181], v[86:89]
	v_mfma_f32_16x16x32_bf16 v[82:85], v[154:157], v[178:181], v[82:85]
	v_mfma_f32_16x16x32_bf16 v[70:73], v[146:149], v[202:205], v[70:73]
	v_mfma_f32_16x16x32_bf16 v[66:69], v[154:157], v[202:205], v[66:69]
	v_mfma_f32_16x16x32_bf16 v[130:133], v[150:153], v[166:169], v[130:133]
	v_mfma_f32_16x16x32_bf16 v[122:125], v[158:161], v[166:169], v[122:125]
	v_mfma_f32_16x16x32_bf16 v[102:105], v[150:153], v[174:177], v[102:105]
	v_mfma_f32_16x16x32_bf16 v[98:101], v[158:161], v[174:177], v[98:101]
	v_mfma_f32_16x16x32_bf16 v[86:89], v[150:153], v[182:185], v[86:89]
	v_mfma_f32_16x16x32_bf16 v[82:85], v[158:161], v[182:185], v[82:85]
	v_mfma_f32_16x16x32_bf16 v[70:73], v[150:153], v[206:209], v[70:73]
	v_mfma_f32_16x16x32_bf16 v[66:69], v[158:161], v[206:209], v[66:69]
	s_setprio 0
	s_barrier
	s_add_i32 s15, s57, s10
	s_mov_b32 m0, s15
	ds_read_b128 v[162:165], v219 offset:16384
	ds_read_b128 v[166:169], v219 offset:17408
	ds_read_b128 v[170:173], v219 offset:18432
	ds_read_b128 v[174:177], v219 offset:19456
	ds_read_b128 v[178:181], v219 offset:20480
	ds_read_b128 v[182:185], v219 offset:21504
	ds_read_b128 v[202:205], v219 offset:22528
	ds_read_b128 v[206:209], v219 offset:23552
	v_lshl_add_u64 v[210:211], s[50:51], 0, v[188:189]
	global_load_lds_dwordx4 v[210:211], off
	s_add_i32 m0, s15, 0x2000
	s_add_u32 s46, s50, 0xb0000
	v_lshl_add_u64 v[212:213], s[50:51], 0, v[192:193]
	s_addc_u32 s47, s51, 0
	s_add_i32 s15, s58, s10
	global_load_lds_dwordx4 v[212:213], off
	v_lshl_add_u64 v[220:221], s[46:47], 0, v[188:189]
	s_mov_b32 m0, s15
	v_lshl_add_u64 v[228:229], s[52:53], 0, v[190:191]
	global_load_lds_dwordx4 v[220:221], off
	v_lshl_add_u64 v[220:221], s[46:47], 0, v[192:193]
	s_add_i32 m0, s15, 0x2000
	s_nop 0
	global_load_lds_dwordx4 v[220:221], off
	v_lshl_add_u64 v[220:221], s[52:53], 0, v[186:187]
	s_mov_b32 m0, s11
	s_nop 0
	global_load_lds_dwordx4 v[220:221], off
	s_mov_b32 m0, s13
	s_nop 0
	global_load_lds_dwordx4 v[228:229], off
	s_waitcnt vmcnt(8)
	s_waitcnt lgkmcnt(0)
	s_barrier
	s_setprio 1
	s_waitcnt lgkmcnt(0)
	v_mfma_f32_16x16x32_bf16 v[62:65], v[106:109], v[162:165], v[62:65]
	v_mfma_f32_16x16x32_bf16 v[58:61], v[126:129], v[162:165], v[58:61]
	v_mfma_f32_16x16x32_bf16 v[46:49], v[106:109], v[170:173], v[46:49]
	v_mfma_f32_16x16x32_bf16 v[42:45], v[126:129], v[170:173], v[42:45]
	v_mfma_f32_16x16x32_bf16 v[30:33], v[106:109], v[178:181], v[30:33]
	v_mfma_f32_16x16x32_bf16 v[26:29], v[126:129], v[178:181], v[26:29]
	v_mfma_f32_16x16x32_bf16 v[14:17], v[106:109], v[202:205], v[14:17]
	v_mfma_f32_16x16x32_bf16 v[10:13], v[126:129], v[202:205], v[10:13]
	v_mfma_f32_16x16x32_bf16 v[62:65], v[110:113], v[166:169], v[62:65]
	v_mfma_f32_16x16x32_bf16 v[58:61], v[138:141], v[166:169], v[58:61]
	v_mfma_f32_16x16x32_bf16 v[46:49], v[110:113], v[174:177], v[46:49]
	v_mfma_f32_16x16x32_bf16 v[42:45], v[138:141], v[174:177], v[42:45]
	v_mfma_f32_16x16x32_bf16 v[30:33], v[110:113], v[182:185], v[30:33]
	v_mfma_f32_16x16x32_bf16 v[26:29], v[138:141], v[182:185], v[26:29]
	v_mfma_f32_16x16x32_bf16 v[14:17], v[110:113], v[206:209], v[14:17]
	v_mfma_f32_16x16x32_bf16 v[10:13], v[138:141], v[206:209], v[10:13]
	s_setprio 0
	s_setprio 1
	v_mfma_f32_16x16x32_bf16 v[54:57], v[146:149], v[162:165], v[54:57]
	v_mfma_f32_16x16x32_bf16 v[50:53], v[154:157], v[162:165], v[50:53]
	v_mfma_f32_16x16x32_bf16 v[38:41], v[146:149], v[170:173], v[38:41]
	v_mfma_f32_16x16x32_bf16 v[34:37], v[154:157], v[170:173], v[34:37]
	v_mfma_f32_16x16x32_bf16 v[22:25], v[146:149], v[178:181], v[22:25]
	v_mfma_f32_16x16x32_bf16 v[18:21], v[154:157], v[178:181], v[18:21]
	v_mfma_f32_16x16x32_bf16 v[6:9], v[146:149], v[202:205], v[6:9]
	v_mfma_f32_16x16x32_bf16 v[2:5], v[154:157], v[202:205], v[2:5]
	v_mfma_f32_16x16x32_bf16 v[54:57], v[150:153], v[166:169], v[54:57]
	v_mfma_f32_16x16x32_bf16 v[50:53], v[158:161], v[166:169], v[50:53]
	v_mfma_f32_16x16x32_bf16 v[38:41], v[150:153], v[174:177], v[38:41]
	v_mfma_f32_16x16x32_bf16 v[34:37], v[158:161], v[174:177], v[34:37]
	v_mfma_f32_16x16x32_bf16 v[22:25], v[150:153], v[182:185], v[22:25]
	v_mfma_f32_16x16x32_bf16 v[18:21], v[158:161], v[182:185], v[18:21]
	v_mfma_f32_16x16x32_bf16 v[6:9], v[150:153], v[206:209], v[6:9]
	v_mfma_f32_16x16x32_bf16 v[2:5], v[158:161], v[206:209], v[2:5]
	s_setprio 0
	s_barrier
	s_add_i32 s15, 0, 0x18000
	s_add_i32 s64, 0, 0x1c000
	v_add_u32_e32 v138, s15, v215
	v_add_u32_e32 v158, s64, v215
	ds_read_b128 v[106:109], v138
	ds_read_b128 v[110:113], v138 offset:1024
	ds_read_b128 v[126:129], v138 offset:2048
	ds_read_b128 v[138:141], v138 offset:3072
	ds_read_b128 v[146:149], v158
	ds_read_b128 v[150:153], v158 offset:1024
	ds_read_b128 v[154:157], v158 offset:2048
	ds_read_b128 v[158:161], v158 offset:3072
	s_add_u32 s46, s52, 0xb0000
	s_addc_u32 s47, s53, 0
	s_mov_b32 m0, s16
	v_lshl_add_u64 v[230:231], s[46:47], 0, v[186:187]
	ds_read_b128 v[162:165], v219 offset:32768
	ds_read_b128 v[166:169], v219 offset:33792
	ds_read_b128 v[170:173], v219 offset:34816
	ds_read_b128 v[174:177], v219 offset:35840
	ds_read_b128 v[178:181], v219 offset:36864
	ds_read_b128 v[182:185], v219 offset:37888
	ds_read_b128 v[202:205], v219 offset:38912
	ds_read_b128 v[206:209], v219 offset:39936
	global_load_lds_dwordx4 v[230:231], off
	v_lshl_add_u64 v[230:231], s[46:47], 0, v[190:191]
	s_mov_b32 m0, s17
	s_nop 0
	global_load_lds_dwordx4 v[230:231], off
	s_waitcnt vmcnt(8)
	s_waitcnt lgkmcnt(0)
	s_barrier
	s_setprio 1
	s_waitcnt lgkmcnt(0)
	v_mfma_f32_16x16x32_bf16 v[142:145], v[106:109], v[162:165], v[142:145]
	v_mfma_f32_16x16x32_bf16 v[134:137], v[126:129], v[162:165], v[134:137]
	v_mfma_f32_16x16x32_bf16 v[118:121], v[106:109], v[170:173], v[118:121]
	v_mfma_f32_16x16x32_bf16 v[114:117], v[126:129], v[170:173], v[114:117]
	v_mfma_f32_16x16x32_bf16 v[94:97], v[106:109], v[178:181], v[94:97]
	v_mfma_f32_16x16x32_bf16 v[90:93], v[126:129], v[178:181], v[90:93]
	v_mfma_f32_16x16x32_bf16 v[78:81], v[106:109], v[202:205], v[78:81]
	v_mfma_f32_16x16x32_bf16 v[74:77], v[126:129], v[202:205], v[74:77]
	v_mfma_f32_16x16x32_bf16 v[142:145], v[110:113], v[166:169], v[142:145]
	v_mfma_f32_16x16x32_bf16 v[134:137], v[138:141], v[166:169], v[134:137]
	v_mfma_f32_16x16x32_bf16 v[118:121], v[110:113], v[174:177], v[118:121]
	v_mfma_f32_16x16x32_bf16 v[114:117], v[138:141], v[174:177], v[114:117]
	v_mfma_f32_16x16x32_bf16 v[94:97], v[110:113], v[182:185], v[94:97]
	v_mfma_f32_16x16x32_bf16 v[90:93], v[138:141], v[182:185], v[90:93]
	v_mfma_f32_16x16x32_bf16 v[78:81], v[110:113], v[206:209], v[78:81]
	v_mfma_f32_16x16x32_bf16 v[74:77], v[138:141], v[206:209], v[74:77]
	s_setprio 0
	s_setprio 1
	v_mfma_f32_16x16x32_bf16 v[130:133], v[146:149], v[162:165], v[130:133]
	v_mfma_f32_16x16x32_bf16 v[122:125], v[154:157], v[162:165], v[122:125]
	v_mfma_f32_16x16x32_bf16 v[102:105], v[146:149], v[170:173], v[102:105]
	v_mfma_f32_16x16x32_bf16 v[98:101], v[154:157], v[170:173], v[98:101]
	v_mfma_f32_16x16x32_bf16 v[86:89], v[146:149], v[178:181], v[86:89]
	v_mfma_f32_16x16x32_bf16 v[82:85], v[154:157], v[178:181], v[82:85]
	v_mfma_f32_16x16x32_bf16 v[70:73], v[146:149], v[202:205], v[70:73]
	v_mfma_f32_16x16x32_bf16 v[66:69], v[154:157], v[202:205], v[66:69]
	v_mfma_f32_16x16x32_bf16 v[130:133], v[150:153], v[166:169], v[130:133]
	v_mfma_f32_16x16x32_bf16 v[122:125], v[158:161], v[166:169], v[122:125]
	v_mfma_f32_16x16x32_bf16 v[102:105], v[150:153], v[174:177], v[102:105]
	v_mfma_f32_16x16x32_bf16 v[98:101], v[158:161], v[174:177], v[98:101]
	v_mfma_f32_16x16x32_bf16 v[86:89], v[150:153], v[182:185], v[86:89]
	v_mfma_f32_16x16x32_bf16 v[82:85], v[158:161], v[182:185], v[82:85]
	v_mfma_f32_16x16x32_bf16 v[70:73], v[150:153], v[206:209], v[70:73]
	v_mfma_f32_16x16x32_bf16 v[66:69], v[158:161], v[206:209], v[66:69]
	s_setprio 0
	s_barrier
	s_add_i32 s15, s15, s10
	s_mov_b32 m0, s15
	ds_read_b128 v[162:165], v219 offset:49152
	ds_read_b128 v[166:169], v219 offset:50176
	ds_read_b128 v[170:173], v219 offset:51200
	ds_read_b128 v[174:177], v219 offset:52224
	ds_read_b128 v[178:181], v219 offset:53248
	ds_read_b128 v[182:185], v219 offset:54272
	ds_read_b128 v[202:205], v219 offset:55296
	ds_read_b128 v[206:209], v219 offset:56320
	v_lshl_add_u64 v[210:211], v[210:211], 0, s[36:37]
	global_load_lds_dwordx4 v[210:211], off
	s_add_i32 m0, s15, 0x2000
	s_add_u32 s46, s50, 0xb0080
	v_lshl_add_u64 v[210:211], v[212:213], 0, s[36:37]
	s_addc_u32 s47, s51, 0
	s_add_i32 s15, s64, s10
	global_load_lds_dwordx4 v[210:211], off
	v_lshl_add_u64 v[210:211], s[46:47], 0, v[188:189]
	s_mov_b32 m0, s15
	s_nop 0
	global_load_lds_dwordx4 v[210:211], off
	v_lshl_add_u64 v[210:211], s[46:47], 0, v[192:193]
	s_add_i32 m0, s15, 0x2000
	s_nop 0
	global_load_lds_dwordx4 v[210:211], off
	v_lshl_add_u64 v[210:211], v[220:221], 0, s[36:37]
	s_mov_b32 m0, s55
	s_nop 0
	global_load_lds_dwordx4 v[210:211], off
	v_lshl_add_u64 v[210:211], v[228:229], 0, s[36:37]
	s_mov_b32 m0, s56
	s_nop 0
	global_load_lds_dwordx4 v[210:211], off
	s_waitcnt vmcnt(8)
	s_waitcnt lgkmcnt(0)
	s_barrier
	s_setprio 1
	s_waitcnt lgkmcnt(0)
	v_mfma_f32_16x16x32_bf16 v[62:65], v[106:109], v[162:165], v[62:65]
	v_mfma_f32_16x16x32_bf16 v[58:61], v[126:129], v[162:165], v[58:61]
	v_mfma_f32_16x16x32_bf16 v[46:49], v[106:109], v[170:173], v[46:49]
	v_mfma_f32_16x16x32_bf16 v[42:45], v[126:129], v[170:173], v[42:45]
	v_mfma_f32_16x16x32_bf16 v[30:33], v[106:109], v[178:181], v[30:33]
	v_mfma_f32_16x16x32_bf16 v[26:29], v[126:129], v[178:181], v[26:29]
	v_mfma_f32_16x16x32_bf16 v[14:17], v[106:109], v[202:205], v[14:17]
	v_mfma_f32_16x16x32_bf16 v[10:13], v[126:129], v[202:205], v[10:13]
	v_mfma_f32_16x16x32_bf16 v[62:65], v[110:113], v[166:169], v[62:65]
	v_mfma_f32_16x16x32_bf16 v[58:61], v[138:141], v[166:169], v[58:61]
	v_mfma_f32_16x16x32_bf16 v[46:49], v[110:113], v[174:177], v[46:49]
	v_mfma_f32_16x16x32_bf16 v[42:45], v[138:141], v[174:177], v[42:45]
	v_mfma_f32_16x16x32_bf16 v[30:33], v[110:113], v[182:185], v[30:33]
	v_mfma_f32_16x16x32_bf16 v[26:29], v[138:141], v[182:185], v[26:29]
	v_mfma_f32_16x16x32_bf16 v[14:17], v[110:113], v[206:209], v[14:17]
	v_mfma_f32_16x16x32_bf16 v[10:13], v[138:141], v[206:209], v[10:13]
	s_setprio 0
	s_setprio 1
	v_mfma_f32_16x16x32_bf16 v[54:57], v[146:149], v[162:165], v[54:57]
	v_mfma_f32_16x16x32_bf16 v[50:53], v[154:157], v[162:165], v[50:53]
	v_mfma_f32_16x16x32_bf16 v[38:41], v[146:149], v[170:173], v[38:41]
	v_mfma_f32_16x16x32_bf16 v[34:37], v[154:157], v[170:173], v[34:37]
	v_mfma_f32_16x16x32_bf16 v[22:25], v[146:149], v[178:181], v[22:25]
	v_mfma_f32_16x16x32_bf16 v[18:21], v[154:157], v[178:181], v[18:21]
	v_mfma_f32_16x16x32_bf16 v[6:9], v[146:149], v[202:205], v[6:9]
	v_mfma_f32_16x16x32_bf16 v[2:5], v[154:157], v[202:205], v[2:5]
	v_mfma_f32_16x16x32_bf16 v[54:57], v[150:153], v[166:169], v[54:57]
	v_mfma_f32_16x16x32_bf16 v[50:53], v[158:161], v[166:169], v[50:53]
	v_mfma_f32_16x16x32_bf16 v[38:41], v[150:153], v[174:177], v[38:41]
	v_mfma_f32_16x16x32_bf16 v[34:37], v[158:161], v[174:177], v[34:37]
	v_mfma_f32_16x16x32_bf16 v[22:25], v[150:153], v[182:185], v[22:25]
	v_mfma_f32_16x16x32_bf16 v[18:21], v[158:161], v[182:185], v[18:21]
	v_mfma_f32_16x16x32_bf16 v[6:9], v[150:153], v[206:209], v[6:9]
	v_mfma_f32_16x16x32_bf16 v[2:5], v[158:161], v[206:209], v[2:5]
	s_setprio 0
	s_barrier
	s_add_i32 s63, s63, 2
	s_add_u32 s12, s12, 0x100
	s_addc_u32 s62, s62, 0
	s_cmp_gt_u32 s63, 41
	s_mov_b64 s[46:47], s[48:49]
	s_cbranch_scc0 .LBB0_1341
	s_and_b64 vcc, exec, s[38:39]
	s_cbranch_vccz .LBB0_1344
	s_barrier

.LBB0_1409:
	s_add_u32 s15, s54, s60
	s_addc_u32 s62, s55, s61
	s_add_u32 s15, s15, 0x100
	s_addc_u32 s62, s62, 0
	s_add_u32 s94, s57, s60
	s_addc_u32 s63, s92, s61
	s_add_i32 s95, 0, 0x10000
	s_cmpk_eq_i32 s60, 0x1500
	s_cselect_b32 s65, s59, s62
	s_cselect_b32 s64, s58, s15
	v_add_u32_e32 v147, s95, v145
	s_cselect_b32 s63, s9, s63
	s_cselect_b32 s62, s8, s94
	s_add_i32 s15, 0, 0x14000
	ds_read_b128 v[148:151], v147
	ds_read_b128 v[152:155], v147 offset:1024
	ds_read_b128 v[156:159], v147 offset:2048
	ds_read_b128 v[160:163], v147 offset:3072
	v_add_u32_e32 v147, s15, v145
	ds_read_b128 v[164:167], v147
	ds_read_b128 v[168:171], v147 offset:1024
	ds_read_b128 v[172:175], v147 offset:2048
	ds_read_b128 v[176:179], v147 offset:3072
	v_lshl_add_u64 v[200:201], v[140:141], 0, s[60:61]
	s_add_i32 m0, s53, 0xc000
	ds_read_b128 v[180:183], v146
	ds_read_b128 v[184:187], v146 offset:1024
	ds_read_b128 v[188:191], v146 offset:2048
	ds_read_b128 v[192:195], v146 offset:3072
	ds_read_b128 v[196:199], v146 offset:4096
	ds_read_b128 v[218:221], v146 offset:5120
	ds_read_b128 v[228:231], v146 offset:6144
	ds_read_b128 v[232:235], v146 offset:7168
	global_load_lds_dwordx4 v[200:201], off
	v_lshl_add_u64 v[200:201], v[142:143], 0, s[60:61]
	s_add_i32 m0, s53, 0xe000
	s_nop 0
	global_load_lds_dwordx4 v[200:201], off
	s_waitcnt vmcnt(8)
	s_waitcnt lgkmcnt(0)
	s_barrier
	s_setprio 1
	s_waitcnt lgkmcnt(0)
	v_mfma_f32_16x16x32_bf16 v[126:129], v[148:151], v[180:183], v[126:129]
	v_mfma_f32_16x16x32_bf16 v[122:125], v[156:159], v[180:183], v[122:125]
	v_mfma_f32_16x16x32_bf16 v[114:117], v[148:151], v[188:191], v[114:117]
	v_mfma_f32_16x16x32_bf16 v[106:109], v[156:159], v[188:191], v[106:109]
	v_mfma_f32_16x16x32_bf16 v[98:101], v[148:151], v[196:199], v[98:101]
	v_mfma_f32_16x16x32_bf16 v[90:93], v[156:159], v[196:199], v[90:93]
	v_mfma_f32_16x16x32_bf16 v[82:85], v[148:151], v[228:231], v[82:85]
	v_mfma_f32_16x16x32_bf16 v[74:77], v[156:159], v[228:231], v[74:77]
	v_mfma_f32_16x16x32_bf16 v[126:129], v[152:155], v[184:187], v[126:129]
	v_mfma_f32_16x16x32_bf16 v[122:125], v[160:163], v[184:187], v[122:125]
	v_mfma_f32_16x16x32_bf16 v[114:117], v[152:155], v[192:195], v[114:117]
	v_mfma_f32_16x16x32_bf16 v[106:109], v[160:163], v[192:195], v[106:109]
	v_mfma_f32_16x16x32_bf16 v[98:101], v[152:155], v[218:221], v[98:101]
	v_mfma_f32_16x16x32_bf16 v[90:93], v[160:163], v[218:221], v[90:93]
	v_mfma_f32_16x16x32_bf16 v[82:85], v[152:155], v[232:235], v[82:85]
	v_mfma_f32_16x16x32_bf16 v[74:77], v[160:163], v[232:235], v[74:77]
	s_setprio 0
	s_setprio 1
	v_mfma_f32_16x16x32_bf16 v[118:121], v[164:167], v[180:183], v[118:121]
	v_mfma_f32_16x16x32_bf16 v[110:113], v[172:175], v[180:183], v[110:113]
	v_mfma_f32_16x16x32_bf16 v[102:105], v[164:167], v[188:191], v[102:105]
	v_mfma_f32_16x16x32_bf16 v[94:97], v[172:175], v[188:191], v[94:97]
	v_mfma_f32_16x16x32_bf16 v[86:89], v[164:167], v[196:199], v[86:89]
	v_mfma_f32_16x16x32_bf16 v[78:81], v[172:175], v[196:199], v[78:81]
	v_mfma_f32_16x16x32_bf16 v[70:73], v[164:167], v[228:231], v[70:73]
	v_mfma_f32_16x16x32_bf16 v[66:69], v[172:175], v[228:231], v[66:69]
	v_mfma_f32_16x16x32_bf16 v[118:121], v[168:171], v[184:187], v[118:121]
	v_mfma_f32_16x16x32_bf16 v[110:113], v[176:179], v[184:187], v[110:113]
	v_mfma_f32_16x16x32_bf16 v[102:105], v[168:171], v[192:195], v[102:105]
	v_mfma_f32_16x16x32_bf16 v[94:97], v[176:179], v[192:195], v[94:97]
	v_mfma_f32_16x16x32_bf16 v[86:89], v[168:171], v[218:221], v[86:89]
	v_mfma_f32_16x16x32_bf16 v[78:81], v[176:179], v[218:221], v[78:81]
	v_mfma_f32_16x16x32_bf16 v[70:73], v[168:171], v[232:235], v[70:73]
	v_mfma_f32_16x16x32_bf16 v[66:69], v[176:179], v[232:235], v[66:69]
	s_setprio 0
	s_barrier
	s_add_i32 s94, s95, s11
	s_mov_b32 m0, s94
	ds_read_b128 v[180:183], v146 offset:16384
	ds_read_b128 v[184:187], v146 offset:17408
	ds_read_b128 v[188:191], v146 offset:18432
	ds_read_b128 v[192:195], v146 offset:19456
	ds_read_b128 v[196:199], v146 offset:20480
	ds_read_b128 v[218:221], v146 offset:21504
	ds_read_b128 v[228:231], v146 offset:22528
	ds_read_b128 v[232:235], v146 offset:23552
	v_lshl_add_u64 v[200:201], s[62:63], 0, v[202:203]
	global_load_lds_dwordx4 v[200:201], off
	s_add_i32 m0, s94, 0x2000
	s_add_u32 s94, s62, 0xb0000
	v_lshl_add_u64 v[210:211], s[62:63], 0, v[130:131]
	s_addc_u32 s95, s63, 0
	s_add_i32 s15, s15, s11
	global_load_lds_dwordx4 v[210:211], off
	v_lshl_add_u64 v[236:237], s[94:95], 0, v[202:203]
	s_mov_b32 m0, s15
	v_lshl_add_u64 v[238:239], s[64:65], 0, v[132:133]
	global_load_lds_dwordx4 v[236:237], off
	v_lshl_add_u64 v[236:237], s[94:95], 0, v[130:131]
	s_add_i32 m0, s15, 0x2000
	s_nop 0
	global_load_lds_dwordx4 v[236:237], off
	v_lshl_add_u64 v[236:237], s[64:65], 0, v[134:135]
	s_mov_b32 m0, s53
	s_nop 0
	global_load_lds_dwordx4 v[236:237], off
	s_mov_b32 m0, s83
	s_nop 0
	global_load_lds_dwordx4 v[238:239], off
	s_waitcnt vmcnt(8)
	s_waitcnt lgkmcnt(0)
	s_barrier
	s_setprio 1
	s_waitcnt lgkmcnt(0)
	v_mfma_f32_16x16x32_bf16 v[62:65], v[148:151], v[180:183], v[62:65]
	v_mfma_f32_16x16x32_bf16 v[58:61], v[156:159], v[180:183], v[58:61]
	v_mfma_f32_16x16x32_bf16 v[50:53], v[148:151], v[188:191], v[50:53]
	v_mfma_f32_16x16x32_bf16 v[42:45], v[156:159], v[188:191], v[42:45]
	v_mfma_f32_16x16x32_bf16 v[34:37], v[148:151], v[196:199], v[34:37]
	v_mfma_f32_16x16x32_bf16 v[26:29], v[156:159], v[196:199], v[26:29]
	v_mfma_f32_16x16x32_bf16 v[18:21], v[148:151], v[228:231], v[18:21]
	v_mfma_f32_16x16x32_bf16 v[10:13], v[156:159], v[228:231], v[10:13]
	v_mfma_f32_16x16x32_bf16 v[62:65], v[152:155], v[184:187], v[62:65]
	v_mfma_f32_16x16x32_bf16 v[58:61], v[160:163], v[184:187], v[58:61]
	v_mfma_f32_16x16x32_bf16 v[50:53], v[152:155], v[192:195], v[50:53]
	v_mfma_f32_16x16x32_bf16 v[42:45], v[160:163], v[192:195], v[42:45]
	v_mfma_f32_16x16x32_bf16 v[34:37], v[152:155], v[218:221], v[34:37]
	v_mfma_f32_16x16x32_bf16 v[26:29], v[160:163], v[218:221], v[26:29]
	v_mfma_f32_16x16x32_bf16 v[18:21], v[152:155], v[232:235], v[18:21]
	v_mfma_f32_16x16x32_bf16 v[10:13], v[160:163], v[232:235], v[10:13]
	s_setprio 0
	s_setprio 1
	v_mfma_f32_16x16x32_bf16 v[54:57], v[164:167], v[180:183], v[54:57]
	v_mfma_f32_16x16x32_bf16 v[46:49], v[172:175], v[180:183], v[46:49]
	v_mfma_f32_16x16x32_bf16 v[38:41], v[164:167], v[188:191], v[38:41]
	v_mfma_f32_16x16x32_bf16 v[30:33], v[172:175], v[188:191], v[30:33]
	v_mfma_f32_16x16x32_bf16 v[22:25], v[164:167], v[196:199], v[22:25]
	v_mfma_f32_16x16x32_bf16 v[14:17], v[172:175], v[196:199], v[14:17]
	v_mfma_f32_16x16x32_bf16 v[6:9], v[164:167], v[228:231], v[6:9]
	v_mfma_f32_16x16x32_bf16 v[2:5], v[172:175], v[228:231], v[2:5]
	v_mfma_f32_16x16x32_bf16 v[54:57], v[168:171], v[184:187], v[54:57]
	v_mfma_f32_16x16x32_bf16 v[46:49], v[176:179], v[184:187], v[46:49]
	v_mfma_f32_16x16x32_bf16 v[38:41], v[168:171], v[192:195], v[38:41]
	v_mfma_f32_16x16x32_bf16 v[30:33], v[176:179], v[192:195], v[30:33]
	v_mfma_f32_16x16x32_bf16 v[22:25], v[168:171], v[218:221], v[22:25]
	v_mfma_f32_16x16x32_bf16 v[14:17], v[176:179], v[218:221], v[14:17]
	v_mfma_f32_16x16x32_bf16 v[6:9], v[168:171], v[232:235], v[6:9]
	v_mfma_f32_16x16x32_bf16 v[2:5], v[176:179], v[232:235], v[2:5]
	s_setprio 0
	s_barrier
	s_add_i32 s15, 0, 0x18000
	v_add_u32_e32 v147, s15, v145
	s_add_i32 s94, 0, 0x1c000
	ds_read_b128 v[148:151], v147
	ds_read_b128 v[152:155], v147 offset:1024
	ds_read_b128 v[156:159], v147 offset:2048
	ds_read_b128 v[160:163], v147 offset:3072
	v_add_u32_e32 v147, s94, v145
	ds_read_b128 v[164:167], v147
	ds_read_b128 v[168:171], v147 offset:1024
	ds_read_b128 v[172:175], v147 offset:2048
	ds_read_b128 v[176:179], v147 offset:3072
	s_add_u32 s64, s64, 0xb0000
	s_addc_u32 s65, s65, 0
	s_mov_b32 m0, s84
	v_lshl_add_u64 v[240:241], s[64:65], 0, v[134:135]
	ds_read_b128 v[180:183], v146 offset:32768
	ds_read_b128 v[184:187], v146 offset:33792
	ds_read_b128 v[188:191], v146 offset:34816
	ds_read_b128 v[192:195], v146 offset:35840
	ds_read_b128 v[196:199], v146 offset:36864
	ds_read_b128 v[218:221], v146 offset:37888
	ds_read_b128 v[228:231], v146 offset:38912
	ds_read_b128 v[232:235], v146 offset:39936
	global_load_lds_dwordx4 v[240:241], off
	v_lshl_add_u64 v[240:241], s[64:65], 0, v[132:133]
	s_mov_b32 m0, s85
	s_nop 0
	global_load_lds_dwordx4 v[240:241], off
	s_waitcnt vmcnt(8)
	s_waitcnt lgkmcnt(0)
	s_barrier
	s_setprio 1
	s_waitcnt lgkmcnt(0)
	v_mfma_f32_16x16x32_bf16 v[126:129], v[148:151], v[180:183], v[126:129]
	v_mfma_f32_16x16x32_bf16 v[122:125], v[156:159], v[180:183], v[122:125]
	v_mfma_f32_16x16x32_bf16 v[114:117], v[148:151], v[188:191], v[114:117]
	v_mfma_f32_16x16x32_bf16 v[106:109], v[156:159], v[188:191], v[106:109]
	v_mfma_f32_16x16x32_bf16 v[98:101], v[148:151], v[196:199], v[98:101]
	v_mfma_f32_16x16x32_bf16 v[90:93], v[156:159], v[196:199], v[90:93]
	v_mfma_f32_16x16x32_bf16 v[82:85], v[148:151], v[228:231], v[82:85]
	v_mfma_f32_16x16x32_bf16 v[74:77], v[156:159], v[228:231], v[74:77]
	v_mfma_f32_16x16x32_bf16 v[126:129], v[152:155], v[184:187], v[126:129]
	v_mfma_f32_16x16x32_bf16 v[122:125], v[160:163], v[184:187], v[122:125]
	v_mfma_f32_16x16x32_bf16 v[114:117], v[152:155], v[192:195], v[114:117]
	v_mfma_f32_16x16x32_bf16 v[106:109], v[160:163], v[192:195], v[106:109]
	v_mfma_f32_16x16x32_bf16 v[98:101], v[152:155], v[218:221], v[98:101]
	v_mfma_f32_16x16x32_bf16 v[90:93], v[160:163], v[218:221], v[90:93]
	v_mfma_f32_16x16x32_bf16 v[82:85], v[152:155], v[232:235], v[82:85]
	v_mfma_f32_16x16x32_bf16 v[74:77], v[160:163], v[232:235], v[74:77]
	s_setprio 0
	s_setprio 1
	v_mfma_f32_16x16x32_bf16 v[118:121], v[164:167], v[180:183], v[118:121]
	v_mfma_f32_16x16x32_bf16 v[110:113], v[172:175], v[180:183], v[110:113]
	v_mfma_f32_16x16x32_bf16 v[102:105], v[164:167], v[188:191], v[102:105]
	v_mfma_f32_16x16x32_bf16 v[94:97], v[172:175], v[188:191], v[94:97]
	v_mfma_f32_16x16x32_bf16 v[86:89], v[164:167], v[196:199], v[86:89]
	v_mfma_f32_16x16x32_bf16 v[78:81], v[172:175], v[196:199], v[78:81]
	v_mfma_f32_16x16x32_bf16 v[70:73], v[164:167], v[228:231], v[70:73]
	v_mfma_f32_16x16x32_bf16 v[66:69], v[172:175], v[228:231], v[66:69]
	v_mfma_f32_16x16x32_bf16 v[118:121], v[168:171], v[184:187], v[118:121]
	v_mfma_f32_16x16x32_bf16 v[110:113], v[176:179], v[184:187], v[110:113]
	v_mfma_f32_16x16x32_bf16 v[102:105], v[168:171], v[192:195], v[102:105]
	v_mfma_f32_16x16x32_bf16 v[94:97], v[176:179], v[192:195], v[94:97]
	v_mfma_f32_16x16x32_bf16 v[86:89], v[168:171], v[218:221], v[86:89]
	v_mfma_f32_16x16x32_bf16 v[78:81], v[176:179], v[218:221], v[78:81]
	v_mfma_f32_16x16x32_bf16 v[70:73], v[168:171], v[232:235], v[70:73]
	v_mfma_f32_16x16x32_bf16 v[66:69], v[176:179], v[232:235], v[66:69]
	s_setprio 0
	s_barrier
	s_add_i32 s15, s15, s11
	s_mov_b32 m0, s15
	ds_read_b128 v[180:183], v146 offset:49152
	ds_read_b128 v[184:187], v146 offset:50176
	ds_read_b128 v[188:191], v146 offset:51200
	ds_read_b128 v[192:195], v146 offset:52224
	ds_read_b128 v[196:199], v146 offset:53248
	ds_read_b128 v[218:221], v146 offset:54272
	ds_read_b128 v[228:231], v146 offset:55296
	ds_read_b128 v[232:235], v146 offset:56320
	v_lshl_add_u64 v[200:201], v[200:201], 0, s[50:51]
	global_load_lds_dwordx4 v[200:201], off
	s_add_i32 m0, s15, 0x2000
	s_add_u32 s62, s62, 0xb0080
	v_lshl_add_u64 v[200:201], v[210:211], 0, s[50:51]
	s_addc_u32 s63, s63, 0
	s_add_i32 s15, s94, s11
	global_load_lds_dwordx4 v[200:201], off
	v_lshl_add_u64 v[200:201], s[62:63], 0, v[202:203]
	s_mov_b32 m0, s15
	s_nop 0
	global_load_lds_dwordx4 v[200:201], off
	v_lshl_add_u64 v[200:201], s[62:63], 0, v[130:131]
	s_add_i32 m0, s15, 0x2000
	s_nop 0
	global_load_lds_dwordx4 v[200:201], off
	v_lshl_add_u64 v[200:201], v[236:237], 0, s[50:51]
	s_mov_b32 m0, s87
	s_nop 0
	global_load_lds_dwordx4 v[200:201], off
	v_lshl_add_u64 v[200:201], v[238:239], 0, s[50:51]
	s_mov_b32 m0, s88
	s_nop 0
	global_load_lds_dwordx4 v[200:201], off
	s_waitcnt vmcnt(8)
	s_waitcnt lgkmcnt(0)
	s_barrier
	s_setprio 1
	s_waitcnt lgkmcnt(0)
	v_mfma_f32_16x16x32_bf16 v[62:65], v[148:151], v[180:183], v[62:65]
	v_mfma_f32_16x16x32_bf16 v[58:61], v[156:159], v[180:183], v[58:61]
	v_mfma_f32_16x16x32_bf16 v[50:53], v[148:151], v[188:191], v[50:53]
	v_mfma_f32_16x16x32_bf16 v[42:45], v[156:159], v[188:191], v[42:45]
	v_mfma_f32_16x16x32_bf16 v[34:37], v[148:151], v[196:199], v[34:37]
	v_mfma_f32_16x16x32_bf16 v[26:29], v[156:159], v[196:199], v[26:29]
	v_mfma_f32_16x16x32_bf16 v[18:21], v[148:151], v[228:231], v[18:21]
	v_mfma_f32_16x16x32_bf16 v[10:13], v[156:159], v[228:231], v[10:13]
	v_mfma_f32_16x16x32_bf16 v[62:65], v[152:155], v[184:187], v[62:65]
	v_mfma_f32_16x16x32_bf16 v[58:61], v[160:163], v[184:187], v[58:61]
	v_mfma_f32_16x16x32_bf16 v[50:53], v[152:155], v[192:195], v[50:53]
	v_mfma_f32_16x16x32_bf16 v[42:45], v[160:163], v[192:195], v[42:45]
	v_mfma_f32_16x16x32_bf16 v[34:37], v[152:155], v[218:221], v[34:37]
	v_mfma_f32_16x16x32_bf16 v[26:29], v[160:163], v[218:221], v[26:29]
	v_mfma_f32_16x16x32_bf16 v[18:21], v[152:155], v[232:235], v[18:21]
	v_mfma_f32_16x16x32_bf16 v[10:13], v[160:163], v[232:235], v[10:13]
	s_setprio 0
	s_setprio 1
	v_mfma_f32_16x16x32_bf16 v[54:57], v[164:167], v[180:183], v[54:57]
	v_mfma_f32_16x16x32_bf16 v[46:49], v[172:175], v[180:183], v[46:49]
	v_mfma_f32_16x16x32_bf16 v[38:41], v[164:167], v[188:191], v[38:41]
	v_mfma_f32_16x16x32_bf16 v[30:33], v[172:175], v[188:191], v[30:33]
	v_mfma_f32_16x16x32_bf16 v[22:25], v[164:167], v[196:199], v[22:25]
	v_mfma_f32_16x16x32_bf16 v[14:17], v[172:175], v[196:199], v[14:17]
	v_mfma_f32_16x16x32_bf16 v[6:9], v[164:167], v[228:231], v[6:9]
	v_mfma_f32_16x16x32_bf16 v[2:5], v[172:175], v[228:231], v[2:5]
	v_mfma_f32_16x16x32_bf16 v[54:57], v[168:171], v[184:187], v[54:57]
	v_mfma_f32_16x16x32_bf16 v[46:49], v[176:179], v[184:187], v[46:49]
	v_mfma_f32_16x16x32_bf16 v[38:41], v[168:171], v[192:195], v[38:41]
	v_mfma_f32_16x16x32_bf16 v[30:33], v[176:179], v[192:195], v[30:33]
	v_mfma_f32_16x16x32_bf16 v[22:25], v[168:171], v[218:221], v[22:25]
	v_mfma_f32_16x16x32_bf16 v[14:17], v[176:179], v[218:221], v[14:17]
	v_mfma_f32_16x16x32_bf16 v[6:9], v[168:171], v[232:235], v[6:9]
	v_mfma_f32_16x16x32_bf16 v[2:5], v[176:179], v[232:235], v[2:5]
	s_setprio 0
	s_barrier
	s_add_i32 s12, s12, 2
	s_add_u32 s60, s60, 0x100
	s_addc_u32 s61, s61, 0
	s_cmp_gt_u32 s12, 41
	s_cbranch_scc0 .LBB0_1409
	s_add_u32 s60, s57, 0xffffff00
	s_addc_u32 s61, s92, -1
	s_and_b64 vcc, exec, s[6:7]
	s_cbranch_vccnz .LBB0_1396
	v_mov_b32_e32 v2, 0
	s_mov_b32 s52, s90
	s_mov_b32 s82, s91
	s_mov_b64 s[54:55], s[58:59]
	s_mov_b32 s89, s56
	v_mov_b32_e32 v3, v2
	v_mov_b32_e32 v4, v2
	v_mov_b32_e32 v5, v2
	v_mov_b32_e32 v6, v2
	v_mov_b32_e32 v7, v2
	v_mov_b32_e32 v8, v2
	v_mov_b32_e32 v9, v2
	v_mov_b32_e32 v14, v2
	v_mov_b32_e32 v15, v2
	v_mov_b32_e32 v16, v2
	v_mov_b32_e32 v17, v2
	v_mov_b32_e32 v22, v2
	v_mov_b32_e32 v23, v2
	v_mov_b32_e32 v24, v2
	v_mov_b32_e32 v25, v2
	v_mov_b32_e32 v30, v2
	v_mov_b32_e32 v31, v2
	v_mov_b32_e32 v32, v2
	v_mov_b32_e32 v33, v2
	v_mov_b32_e32 v38, v2
	v_mov_b32_e32 v39, v2
	v_mov_b32_e32 v40, v2
	v_mov_b32_e32 v41, v2
	v_mov_b32_e32 v46, v2
	v_mov_b32_e32 v47, v2
	v_mov_b32_e32 v48, v2
	v_mov_b32_e32 v49, v2
	v_mov_b32_e32 v54, v2
	v_mov_b32_e32 v55, v2
	v_mov_b32_e32 v56, v2
	v_mov_b32_e32 v57, v2
	v_mov_b32_e32 v10, v2
	v_mov_b32_e32 v11, v2
	v_mov_b32_e32 v12, v2
	v_mov_b32_e32 v13, v2
	v_mov_b32_e32 v18, v2
	v_mov_b32_e32 v19, v2
	v_mov_b32_e32 v20, v2
	v_mov_b32_e32 v21, v2
	v_mov_b32_e32 v26, v2
	v_mov_b32_e32 v27, v2
	v_mov_b32_e32 v28, v2
	v_mov_b32_e32 v29, v2
	v_mov_b32_e32 v34, v2
	v_mov_b32_e32 v35, v2
	v_mov_b32_e32 v36, v2
	v_mov_b32_e32 v37, v2
	v_mov_b32_e32 v42, v2
	v_mov_b32_e32 v43, v2
	v_mov_b32_e32 v44, v2
	v_mov_b32_e32 v45, v2
	v_mov_b32_e32 v50, v2
	v_mov_b32_e32 v51, v2
	v_mov_b32_e32 v52, v2
	v_mov_b32_e32 v53, v2
	v_mov_b32_e32 v58, v2
	v_mov_b32_e32 v59, v2
	v_mov_b32_e32 v60, v2
	v_mov_b32_e32 v61, v2
	v_mov_b32_e32 v62, v2
	v_mov_b32_e32 v63, v2
	v_mov_b32_e32 v64, v2
	v_mov_b32_e32 v65, v2
	v_mov_b32_e32 v66, v2
	v_mov_b32_e32 v67, v2
	v_mov_b32_e32 v68, v2
	v_mov_b32_e32 v69, v2
	v_mov_b32_e32 v70, v2
	v_mov_b32_e32 v71, v2
	v_mov_b32_e32 v72, v2
	v_mov_b32_e32 v73, v2
	v_mov_b32_e32 v78, v2
	v_mov_b32_e32 v79, v2
	v_mov_b32_e32 v80, v2
	v_mov_b32_e32 v81, v2
	v_mov_b32_e32 v86, v2
	v_mov_b32_e32 v87, v2
	v_mov_b32_e32 v88, v2
	v_mov_b32_e32 v89, v2
	v_mov_b32_e32 v94, v2
	v_mov_b32_e32 v95, v2
	v_mov_b32_e32 v96, v2
	v_mov_b32_e32 v97, v2
	v_mov_b32_e32 v102, v2
	v_mov_b32_e32 v103, v2
	v_mov_b32_e32 v104, v2
	v_mov_b32_e32 v105, v2
	v_mov_b32_e32 v110, v2
	v_mov_b32_e32 v111, v2
	v_mov_b32_e32 v112, v2
	v_mov_b32_e32 v113, v2
	v_mov_b32_e32 v118, v2
	v_mov_b32_e32 v119, v2
	v_mov_b32_e32 v120, v2
	v_mov_b32_e32 v121, v2
	v_mov_b32_e32 v74, v2
	v_mov_b32_e32 v75, v2
	v_mov_b32_e32 v76, v2
	v_mov_b32_e32 v77, v2
	v_mov_b32_e32 v82, v2
	v_mov_b32_e32 v83, v2
	v_mov_b32_e32 v84, v2
	v_mov_b32_e32 v85, v2
	v_mov_b32_e32 v90, v2
	v_mov_b32_e32 v91, v2
	v_mov_b32_e32 v92, v2
	v_mov_b32_e32 v93, v2
	v_mov_b32_e32 v98, v2
	v_mov_b32_e32 v99, v2
	v_mov_b32_e32 v100, v2
	v_mov_b32_e32 v101, v2
	v_mov_b32_e32 v106, v2
	v_mov_b32_e32 v107, v2
	v_mov_b32_e32 v108, v2
	v_mov_b32_e32 v109, v2
	v_mov_b32_e32 v114, v2
	v_mov_b32_e32 v115, v2
	v_mov_b32_e32 v116, v2
	v_mov_b32_e32 v117, v2
	v_mov_b32_e32 v122, v2
	v_mov_b32_e32 v123, v2
	v_mov_b32_e32 v124, v2
	v_mov_b32_e32 v125, v2
	v_mov_b32_e32 v126, v2
	v_mov_b32_e32 v127, v2
	v_mov_b32_e32 v128, v2
	v_mov_b32_e32 v129, v2
	s_andn2_b64 vcc, exec, s[0:1]
	s_cbranch_vccnz .LBB0_1397
